# EpiFFN: conv chains start with fma(x,w1,bias) and accumulate both neighbour taps with v_fmac_dpp (3 ops instead of 4); remaining mov_dpp+fmac pairs folded
# speedup vs baseline: 1.0178x; 1.0025x over previous
.LBB0_1404:
	s_add_u32 s16, s10, 0xfffc0080
	s_addc_u32 s17, s11, -1
	s_add_i32 s41, 0, 0x10000
	v_add_u32_e32 v132, s41, v198
	ds_read_b128 v[116:119], v132
	ds_read_b128 v[124:127], v132 offset:1024
	ds_read_b128 v[128:131], v132 offset:2048
	ds_read_b128 v[132:135], v132 offset:3072
	s_cmp_eq_u32 s40, 12
	s_cselect_b32 s35, s6, s17
	s_cselect_b32 s34, s31, s16
	s_cselect_b32 s17, s5, s39
	s_cselect_b32 s16, s36, s37
	v_lshl_add_u64 v[186:187], s[10:11], 0, v[176:177]
	s_add_i32 m0, s33, 0xc000
	ds_read_b128 v[136:139], v199
	ds_read_b128 v[140:143], v199 offset:1024
	ds_read_b128 v[144:147], v199 offset:2048
	ds_read_b128 v[148:151], v199 offset:3072
	ds_read_b128 v[152:155], v199 offset:4096
	ds_read_b128 v[178:181], v199 offset:5120
	ds_read_b128 v[182:185], v199 offset:6144
	ds_read_b128 v[200:203], v199 offset:7168
	global_load_lds_dwordx4 v[186:187], off
	v_lshl_add_u64 v[186:187], s[10:11], 0, v[174:175]
	s_add_i32 m0, s33, 0xe000
	s_nop 0
	global_load_lds_dwordx4 v[186:187], off
	s_waitcnt lgkmcnt(8)
	s_barrier
	s_waitcnt lgkmcnt(0)
	s_setprio 1
	s_waitcnt lgkmcnt(0)
	v_mfma_f32_16x16x32_bf16 v[160:163], v[116:119], v[136:139], v[160:163]
	v_mfma_f32_16x16x32_bf16 v[60:63], v[128:131], v[136:139], v[60:63]
	v_mfma_f32_16x16x32_bf16 v[120:123], v[116:119], v[144:147], v[120:123]
	v_mfma_f32_16x16x32_bf16 v[52:55], v[128:131], v[144:147], v[52:55]
	v_mfma_f32_16x16x32_bf16 v[108:111], v[116:119], v[152:155], v[108:111]
	v_mfma_f32_16x16x32_bf16 v[44:47], v[128:131], v[152:155], v[44:47]
	v_mfma_f32_16x16x32_bf16 v[100:103], v[116:119], v[182:185], v[100:103]
	v_mfma_f32_16x16x32_bf16 v[36:39], v[128:131], v[182:185], v[36:39]
	v_mfma_f32_16x16x32_bf16 v[160:163], v[124:127], v[140:143], v[160:163]
	v_mfma_f32_16x16x32_bf16 v[60:63], v[132:135], v[140:143], v[60:63]
	v_mfma_f32_16x16x32_bf16 v[120:123], v[124:127], v[148:151], v[120:123]
	v_mfma_f32_16x16x32_bf16 v[52:55], v[132:135], v[148:151], v[52:55]
	v_mfma_f32_16x16x32_bf16 v[108:111], v[124:127], v[178:181], v[108:111]
	v_mfma_f32_16x16x32_bf16 v[44:47], v[132:135], v[178:181], v[44:47]
	v_mfma_f32_16x16x32_bf16 v[100:103], v[124:127], v[200:203], v[100:103]
	v_mfma_f32_16x16x32_bf16 v[36:39], v[132:135], v[200:203], v[36:39]
	s_setprio 0
	s_barrier
	s_add_i32 s48, 0, 0x14000
	s_add_i32 s41, s41, s27
	v_add_u32_e32 v164, s48, v198
	v_lshl_add_u64 v[186:187], s[16:17], 0, v[172:173]
	s_mov_b32 m0, s41
	ds_read_b128 v[204:207], v164
	ds_read_b128 v[208:211], v164 offset:1024
	ds_read_b128 v[212:215], v164 offset:2048
	ds_read_b128 v[216:219], v164 offset:3072
	global_load_lds_dwordx4 v[186:187], off
	v_lshl_add_u64 v[186:187], s[16:17], 0, v[168:169]
	s_add_i32 m0, s41, 0x2000
	s_nop 0
	global_load_lds_dwordx4 v[186:187], off
	s_barrier
	s_waitcnt lgkmcnt(0)
	s_setprio 1
	s_waitcnt lgkmcnt(0)
	v_mfma_f32_16x16x32_bf16 v[156:159], v[204:207], v[136:139], v[156:159]
	v_mfma_f32_16x16x32_bf16 v[56:59], v[212:215], v[136:139], v[56:59]
	v_mfma_f32_16x16x32_bf16 v[112:115], v[204:207], v[144:147], v[112:115]
	v_mfma_f32_16x16x32_bf16 v[48:51], v[212:215], v[144:147], v[48:51]
	v_mfma_f32_16x16x32_bf16 v[104:107], v[204:207], v[152:155], v[104:107]
	v_mfma_f32_16x16x32_bf16 v[40:43], v[212:215], v[152:155], v[40:43]
	v_mfma_f32_16x16x32_bf16 v[96:99], v[204:207], v[182:185], v[96:99]
	v_mfma_f32_16x16x32_bf16 v[32:35], v[212:215], v[182:185], v[32:35]
	v_mfma_f32_16x16x32_bf16 v[156:159], v[208:211], v[140:143], v[156:159]
	v_mfma_f32_16x16x32_bf16 v[56:59], v[216:219], v[140:143], v[56:59]
	v_mfma_f32_16x16x32_bf16 v[112:115], v[208:211], v[148:151], v[112:115]
	v_mfma_f32_16x16x32_bf16 v[48:51], v[216:219], v[148:151], v[48:51]
	v_mfma_f32_16x16x32_bf16 v[104:107], v[208:211], v[178:181], v[104:107]
	v_mfma_f32_16x16x32_bf16 v[40:43], v[216:219], v[178:181], v[40:43]
	v_mfma_f32_16x16x32_bf16 v[96:99], v[208:211], v[200:203], v[96:99]
	v_mfma_f32_16x16x32_bf16 v[32:35], v[216:219], v[200:203], v[32:35]
	s_setprio 0
	s_mov_b32 m0, s33
	v_lshl_add_u64 v[186:187], s[34:35], 0, v[170:171]
	s_barrier
	ds_read_b128 v[136:139], v199 offset:16384
	ds_read_b128 v[140:143], v199 offset:17408
	ds_read_b128 v[144:147], v199 offset:18432
	ds_read_b128 v[148:151], v199 offset:19456
	ds_read_b128 v[152:155], v199 offset:20480
	ds_read_b128 v[178:181], v199 offset:21504
	ds_read_b128 v[182:185], v199 offset:22528
	ds_read_b128 v[200:203], v199 offset:23552
	global_load_lds_dwordx4 v[186:187], off
	v_lshl_add_u64 v[220:221], s[34:35], 0, v[166:167]
	s_mov_b32 m0, s2
	s_nop 0
	global_load_lds_dwordx4 v[220:221], off
	s_barrier
	s_waitcnt lgkmcnt(0)
	s_setprio 1
	s_waitcnt lgkmcnt(0)
	v_mfma_f32_16x16x32_bf16 v[92:95], v[116:119], v[136:139], v[92:95]
	v_mfma_f32_16x16x32_bf16 v[28:31], v[128:131], v[136:139], v[28:31]
	v_mfma_f32_16x16x32_bf16 v[84:87], v[116:119], v[144:147], v[84:87]
	v_mfma_f32_16x16x32_bf16 v[20:23], v[128:131], v[144:147], v[20:23]
	v_mfma_f32_16x16x32_bf16 v[76:79], v[116:119], v[152:155], v[76:79]
	v_mfma_f32_16x16x32_bf16 v[12:15], v[128:131], v[152:155], v[12:15]
	v_mfma_f32_16x16x32_bf16 v[68:71], v[116:119], v[182:185], v[68:71]
	v_mfma_f32_16x16x32_bf16 v[4:7], v[128:131], v[182:185], v[4:7]
	v_mfma_f32_16x16x32_bf16 v[92:95], v[124:127], v[140:143], v[92:95]
	v_mfma_f32_16x16x32_bf16 v[28:31], v[132:135], v[140:143], v[28:31]
	v_mfma_f32_16x16x32_bf16 v[84:87], v[124:127], v[148:151], v[84:87]
	v_mfma_f32_16x16x32_bf16 v[20:23], v[132:135], v[148:151], v[20:23]
	v_mfma_f32_16x16x32_bf16 v[76:79], v[124:127], v[178:181], v[76:79]
	v_mfma_f32_16x16x32_bf16 v[12:15], v[132:135], v[178:181], v[12:15]
	v_mfma_f32_16x16x32_bf16 v[68:71], v[124:127], v[200:203], v[68:71]
	v_mfma_f32_16x16x32_bf16 v[4:7], v[132:135], v[200:203], v[4:7]
	s_setprio 0
	s_barrier
	s_add_u32 s52, s16, 0x4000
	s_addc_u32 s53, s17, 0
	s_add_i32 s41, s48, s27
	v_lshl_add_u64 v[116:117], s[52:53], 0, v[172:173]
	s_mov_b32 m0, s41
	s_nop 0
	global_load_lds_dwordx4 v[116:117], off
	v_lshl_add_u64 v[116:117], s[52:53], 0, v[168:169]
	s_add_i32 m0, s41, 0x2000
	s_nop 0
	global_load_lds_dwordx4 v[116:117], off
	s_waitcnt vmcnt(6)
	s_barrier
	s_setprio 1
	v_mfma_f32_16x16x32_bf16 v[88:91], v[204:207], v[136:139], v[88:91]
	v_mfma_f32_16x16x32_bf16 v[24:27], v[212:215], v[136:139], v[24:27]
	v_mfma_f32_16x16x32_bf16 v[80:83], v[204:207], v[144:147], v[80:83]
	v_mfma_f32_16x16x32_bf16 v[16:19], v[212:215], v[144:147], v[16:19]
	v_mfma_f32_16x16x32_bf16 v[72:75], v[204:207], v[152:155], v[72:75]
	v_mfma_f32_16x16x32_bf16 v[8:11], v[212:215], v[152:155], v[8:11]
	v_mfma_f32_16x16x32_bf16 v[64:67], v[204:207], v[182:185], v[64:67]
	v_mfma_f32_16x16x32_bf16 v[0:3], v[212:215], v[182:185], v[0:3]
	v_mfma_f32_16x16x32_bf16 v[88:91], v[208:211], v[140:143], v[88:91]
	v_mfma_f32_16x16x32_bf16 v[24:27], v[216:219], v[140:143], v[24:27]
	v_mfma_f32_16x16x32_bf16 v[80:83], v[208:211], v[148:151], v[80:83]
	v_mfma_f32_16x16x32_bf16 v[16:19], v[216:219], v[148:151], v[16:19]
	v_mfma_f32_16x16x32_bf16 v[72:75], v[208:211], v[178:181], v[72:75]
	v_mfma_f32_16x16x32_bf16 v[8:11], v[216:219], v[178:181], v[8:11]
	v_mfma_f32_16x16x32_bf16 v[64:67], v[208:211], v[200:203], v[64:67]
	v_mfma_f32_16x16x32_bf16 v[0:3], v[216:219], v[200:203], v[0:3]
	s_setprio 0
	s_add_i32 s41, 0, 0x18000
	v_add_u32_e32 v132, s41, v198
	s_barrier
	ds_read_b128 v[116:119], v132
	ds_read_b128 v[124:127], v132 offset:1024
	ds_read_b128 v[128:131], v132 offset:2048
	ds_read_b128 v[132:135], v132 offset:3072
	s_add_u32 s34, s34, 0x40000
	s_addc_u32 s35, s35, 0
	s_mov_b32 m0, s78
	v_lshl_add_u64 v[204:205], s[34:35], 0, v[170:171]
	ds_read_b128 v[136:139], v199 offset:32768
	ds_read_b128 v[140:143], v199 offset:33792
	ds_read_b128 v[144:147], v199 offset:34816
	ds_read_b128 v[148:151], v199 offset:35840
	ds_read_b128 v[152:155], v199 offset:36864
	ds_read_b128 v[178:181], v199 offset:37888
	ds_read_b128 v[182:185], v199 offset:38912
	ds_read_b128 v[200:203], v199 offset:39936
	global_load_lds_dwordx4 v[204:205], off
	v_lshl_add_u64 v[204:205], s[34:35], 0, v[166:167]
	s_mov_b32 m0, s79
	s_nop 0
	global_load_lds_dwordx4 v[204:205], off
	s_waitcnt lgkmcnt(8)
	s_barrier
	s_waitcnt lgkmcnt(0)
	s_setprio 1
	s_waitcnt lgkmcnt(0)
	v_mfma_f32_16x16x32_bf16 v[160:163], v[116:119], v[136:139], v[160:163]
	v_mfma_f32_16x16x32_bf16 v[60:63], v[128:131], v[136:139], v[60:63]
	v_mfma_f32_16x16x32_bf16 v[120:123], v[116:119], v[144:147], v[120:123]
	v_mfma_f32_16x16x32_bf16 v[52:55], v[128:131], v[144:147], v[52:55]
	v_mfma_f32_16x16x32_bf16 v[108:111], v[116:119], v[152:155], v[108:111]
	v_mfma_f32_16x16x32_bf16 v[44:47], v[128:131], v[152:155], v[44:47]
	v_mfma_f32_16x16x32_bf16 v[100:103], v[116:119], v[182:185], v[100:103]
	v_mfma_f32_16x16x32_bf16 v[36:39], v[128:131], v[182:185], v[36:39]
	v_mfma_f32_16x16x32_bf16 v[160:163], v[124:127], v[140:143], v[160:163]
	v_mfma_f32_16x16x32_bf16 v[60:63], v[132:135], v[140:143], v[60:63]
	v_mfma_f32_16x16x32_bf16 v[120:123], v[124:127], v[148:151], v[120:123]
	v_mfma_f32_16x16x32_bf16 v[52:55], v[132:135], v[148:151], v[52:55]
	v_mfma_f32_16x16x32_bf16 v[108:111], v[124:127], v[178:181], v[108:111]
	v_mfma_f32_16x16x32_bf16 v[44:47], v[132:135], v[178:181], v[44:47]
	v_mfma_f32_16x16x32_bf16 v[100:103], v[124:127], v[200:203], v[100:103]
	v_mfma_f32_16x16x32_bf16 v[36:39], v[132:135], v[200:203], v[36:39]
	s_setprio 0
	s_barrier
	s_add_i32 s48, 0, 0x1c000
	s_add_u32 s34, s16, 0x8000
	s_addc_u32 s35, s17, 0
	s_add_i32 s41, s41, s27
	v_add_u32_e32 v164, s48, v198
	v_lshl_add_u64 v[222:223], s[34:35], 0, v[172:173]
	s_mov_b32 m0, s41
	ds_read_b128 v[204:207], v164
	ds_read_b128 v[208:211], v164 offset:1024
	ds_read_b128 v[212:215], v164 offset:2048
	ds_read_b128 v[216:219], v164 offset:3072
	global_load_lds_dwordx4 v[222:223], off
	v_lshl_add_u64 v[222:223], s[34:35], 0, v[168:169]
	s_add_i32 m0, s41, 0x2000
	s_nop 0
	global_load_lds_dwordx4 v[222:223], off
	s_barrier
	s_waitcnt lgkmcnt(0)
	s_setprio 1
	s_waitcnt lgkmcnt(0)
	v_mfma_f32_16x16x32_bf16 v[156:159], v[204:207], v[136:139], v[156:159]
	v_mfma_f32_16x16x32_bf16 v[56:59], v[212:215], v[136:139], v[56:59]
	v_mfma_f32_16x16x32_bf16 v[112:115], v[204:207], v[144:147], v[112:115]
	v_mfma_f32_16x16x32_bf16 v[48:51], v[212:215], v[144:147], v[48:51]
	v_mfma_f32_16x16x32_bf16 v[104:107], v[204:207], v[152:155], v[104:107]
	v_mfma_f32_16x16x32_bf16 v[40:43], v[212:215], v[152:155], v[40:43]
	v_mfma_f32_16x16x32_bf16 v[96:99], v[204:207], v[182:185], v[96:99]
	v_mfma_f32_16x16x32_bf16 v[32:35], v[212:215], v[182:185], v[32:35]
	v_mfma_f32_16x16x32_bf16 v[156:159], v[208:211], v[140:143], v[156:159]
	v_mfma_f32_16x16x32_bf16 v[56:59], v[216:219], v[140:143], v[56:59]
	v_mfma_f32_16x16x32_bf16 v[112:115], v[208:211], v[148:151], v[112:115]
	v_mfma_f32_16x16x32_bf16 v[48:51], v[216:219], v[148:151], v[48:51]
	v_mfma_f32_16x16x32_bf16 v[104:107], v[208:211], v[178:181], v[104:107]
	v_mfma_f32_16x16x32_bf16 v[40:43], v[216:219], v[178:181], v[40:43]
	v_mfma_f32_16x16x32_bf16 v[96:99], v[208:211], v[200:203], v[96:99]
	v_mfma_f32_16x16x32_bf16 v[32:35], v[216:219], v[200:203], v[32:35]
	s_setprio 0
	s_mov_b32 m0, s82
	v_lshl_add_u64 v[186:187], v[186:187], 0, s[18:19]
	s_barrier
	ds_read_b128 v[136:139], v199 offset:49152
	ds_read_b128 v[140:143], v199 offset:50176
	ds_read_b128 v[144:147], v199 offset:51200
	ds_read_b128 v[148:151], v199 offset:52224
	ds_read_b128 v[152:155], v199 offset:53248
	ds_read_b128 v[178:181], v199 offset:54272
	ds_read_b128 v[182:185], v199 offset:55296
	ds_read_b128 v[200:203], v199 offset:56320
	global_load_lds_dwordx4 v[186:187], off
	v_lshl_add_u64 v[186:187], v[220:221], 0, s[18:19]
	s_mov_b32 m0, s83
	s_nop 0
	global_load_lds_dwordx4 v[186:187], off
	s_barrier
	s_waitcnt lgkmcnt(0)
	s_setprio 1
	s_waitcnt lgkmcnt(0)
	v_mfma_f32_16x16x32_bf16 v[92:95], v[116:119], v[136:139], v[92:95]
	v_mfma_f32_16x16x32_bf16 v[28:31], v[128:131], v[136:139], v[28:31]
	v_mfma_f32_16x16x32_bf16 v[84:87], v[116:119], v[144:147], v[84:87]
	v_mfma_f32_16x16x32_bf16 v[20:23], v[128:131], v[144:147], v[20:23]
	v_mfma_f32_16x16x32_bf16 v[76:79], v[116:119], v[152:155], v[76:79]
	v_mfma_f32_16x16x32_bf16 v[12:15], v[128:131], v[152:155], v[12:15]
	v_mfma_f32_16x16x32_bf16 v[68:71], v[116:119], v[182:185], v[68:71]
	v_mfma_f32_16x16x32_bf16 v[4:7], v[128:131], v[182:185], v[4:7]
	v_mfma_f32_16x16x32_bf16 v[92:95], v[124:127], v[140:143], v[92:95]
	v_mfma_f32_16x16x32_bf16 v[28:31], v[132:135], v[140:143], v[28:31]
	v_mfma_f32_16x16x32_bf16 v[84:87], v[124:127], v[148:151], v[84:87]
	v_mfma_f32_16x16x32_bf16 v[20:23], v[132:135], v[148:151], v[20:23]
	v_mfma_f32_16x16x32_bf16 v[76:79], v[124:127], v[178:181], v[76:79]
	v_mfma_f32_16x16x32_bf16 v[12:15], v[132:135], v[178:181], v[12:15]
	v_mfma_f32_16x16x32_bf16 v[68:71], v[124:127], v[200:203], v[68:71]
	v_mfma_f32_16x16x32_bf16 v[4:7], v[132:135], v[200:203], v[4:7]
	s_setprio 0
	s_barrier
	s_add_u32 s16, s16, 0xc000
	s_addc_u32 s17, s17, 0
	s_add_i32 s34, s48, s27
	v_lshl_add_u64 v[116:117], s[16:17], 0, v[172:173]
	s_mov_b32 m0, s34
	s_nop 0
	global_load_lds_dwordx4 v[116:117], off
	v_lshl_add_u64 v[116:117], s[16:17], 0, v[168:169]
	s_add_i32 m0, s34, 0x2000
	s_nop 0
	global_load_lds_dwordx4 v[116:117], off
	s_waitcnt vmcnt(6)
	s_barrier
	s_setprio 1
	v_mfma_f32_16x16x32_bf16 v[88:91], v[204:207], v[136:139], v[88:91]
	v_mfma_f32_16x16x32_bf16 v[24:27], v[212:215], v[136:139], v[24:27]
	v_mfma_f32_16x16x32_bf16 v[80:83], v[204:207], v[144:147], v[80:83]
	v_mfma_f32_16x16x32_bf16 v[16:19], v[212:215], v[144:147], v[16:19]
	v_mfma_f32_16x16x32_bf16 v[72:75], v[204:207], v[152:155], v[72:75]
	v_mfma_f32_16x16x32_bf16 v[8:11], v[212:215], v[152:155], v[8:11]
	v_mfma_f32_16x16x32_bf16 v[64:67], v[204:207], v[182:185], v[64:67]
	v_mfma_f32_16x16x32_bf16 v[0:3], v[212:215], v[182:185], v[0:3]
	v_mfma_f32_16x16x32_bf16 v[88:91], v[208:211], v[140:143], v[88:91]
	v_mfma_f32_16x16x32_bf16 v[24:27], v[216:219], v[140:143], v[24:27]
	v_mfma_f32_16x16x32_bf16 v[80:83], v[208:211], v[148:151], v[80:83]
	v_mfma_f32_16x16x32_bf16 v[16:19], v[216:219], v[148:151], v[16:19]
	v_mfma_f32_16x16x32_bf16 v[72:75], v[208:211], v[178:181], v[72:75]
	v_mfma_f32_16x16x32_bf16 v[8:11], v[216:219], v[178:181], v[8:11]
	v_mfma_f32_16x16x32_bf16 v[64:67], v[208:211], v[200:203], v[64:67]
	v_mfma_f32_16x16x32_bf16 v[0:3], v[216:219], v[200:203], v[0:3]
	s_setprio 0
	s_add_i32 s40, s40, 2
	s_add_u32 s37, s37, 0x10000
	s_addc_u32 s39, s39, 0
	s_add_u32 s10, s10, 0x100
	s_addc_u32 s11, s11, 0
	s_cmp_gt_u32 s40, 13
	s_barrier
	s_cbranch_scc0 .LBB0_1404
	v_mov_b32_e32 v116, v188
	s_lshl_b32 s6, s38, 7
	v_readfirstlane_b32 s10, v116
	s_lshr_b32 s5, s10, 1
	v_and_b32_e32 v200, 15, v116
	s_and_b32 s5, s5, 0x60
	v_lshrrev_b32_e32 v116, 1, v116
	s_or_b32 s6, s5, s6
	v_and_b32_e32 v116, 24, v116
	v_or_b32_e32 v182, s6, v116
	v_ashrrev_i32_e32 v183, 31, v182
	v_lshlrev_b64 v[118:119], 2, v[182:183]
	v_lshl_add_u64 v[184:185], s[42:43], 0, v[118:119]
	global_load_dwordx4 v[124:127], v[184:185], off
	v_lshl_add_u64 v[128:129], s[58:59], 0, v[118:119]
	global_load_dwordx4 v[128:131], v[128:129], off
	v_lshl_add_u64 v[132:133], s[60:61], 0, v[118:119]
	global_load_dwordx4 v[132:135], v[132:133], off
	v_lshl_add_u64 v[186:187], s[46:47], 0, v[118:119]
	global_load_dwordx4 v[136:139], v[186:187], off
	v_lshl_add_u64 v[140:141], s[12:13], 0, v[118:119]
	global_load_dwordx4 v[140:143], v[140:141], off
	v_lshl_add_u64 v[144:145], s[50:51], 0, v[118:119]
	global_load_dwordx4 v[144:147], v[144:145], off
	v_lshl_add_u64 v[148:149], s[20:21], 0, v[118:119]
	global_load_dwordx4 v[148:151], v[148:149], off
	v_lshl_add_u64 v[118:119], s[44:45], 0, v[118:119]
	global_load_dwordx4 v[152:155], v[118:119], off
	v_cmp_eq_u32_e32 vcc, 15, v200
	v_cmp_eq_u32_e64 s[34:35], 0, v200
	s_nop 0
	v_cndmask_b32_e64 v117, v160, 0, vcc
	v_cndmask_b32_e64 v118, v160, v120, s[34:35]
	v_cndmask_b32_e64 v164, v156, v112, s[34:35]
	s_nop 0
	v_mov_b32_dpp v119, v118 row_ror:15 row_mask:0xf bank_mask:0xf
	v_cndmask_b32_e64 v118, v156, 0, vcc
	v_mov_b32_dpp v178, v164 row_ror:15 row_mask:0xf bank_mask:0xf
	v_mov_b32_e32 v180, v165
	s_lshl_b32 s11, s7, 8
	s_ashr_i32 s7, s10, 2
	s_andn2_b32 s7, s7, 63
	s_add_i32 s31, s7, s11
	v_mov_b32_e32 v181, v165
	s_ashr_i32 s10, s31, 6
	s_ashr_i32 s11, s10, 31
	s_lshl_b32 s16, s38, 8
	s_lshl_b64 s[52:53], s[10:11], 2
	v_cmp_gt_u32_e64 s[36:37], 2, v200
	s_ashr_i32 s17, s16, 31
	v_or_b32_e32 v183, s52, v200
	s_waitcnt vmcnt(0)
	v_mul_f32_dpp v117, v117, v124 row_ror:1 row_mask:0xf bank_mask:0xf bound_ctrl:1
	v_fmac_f32_e32 v117, v160, v128
	v_fmac_f32_e32 v117, v132, v119
	v_add_f32_e32 v117, v136, v117
	v_mul_f32_e32 v119, 0xbfb8aa3b, v117
	v_exp_f32_e32 v119, v119
	v_mul_f32_dpp v118, v118, v140 row_ror:1 row_mask:0xf bank_mask:0xf bound_ctrl:1
	v_fmac_f32_e32 v118, v156, v144
	v_add_f32_e32 v119, 1.0, v119
	v_rcp_f32_e32 v119, v119
	v_fmac_f32_e32 v118, v148, v178
	v_add_f32_e32 v118, v152, v118
	v_cndmask_b32_e64 v178, v157, v113, s[34:35]
	v_mul_f32_e32 v117, v117, v119
	v_mul_f32_e32 v117, v118, v117
	v_cndmask_b32_e64 v224, v161, 0, vcc
	v_cndmask_b32_e64 v119, v161, v121, s[34:35]
	v_mov_b32_dpp v179, v178 row_ror:15 row_mask:0xf bank_mask:0xf
	v_fma_f32 v118, v161, v129, v137
	v_fmac_f32_dpp v118, v224, v125 row_ror:1 row_mask:0xf bank_mask:0xf bound_ctrl:1
	v_fmac_f32_dpp v118, v119, v133 row_ror:15 row_mask:0xf bank_mask:0xf
	v_mul_f32_e32 v164, 0xbfb8aa3b, v118
	v_exp_f32_e32 v164, v164
	v_cndmask_b32_e64 v224, v157, 0, vcc
	v_add_f32_e32 v164, 1.0, v164
	v_rcp_f32_e32 v164, v164
	v_fma_f32 v119, v157, v145, v153
	v_fmac_f32_dpp v119, v224, v141 row_ror:1 row_mask:0xf bank_mask:0xf bound_ctrl:1
	v_fmac_f32_e32 v119, v149, v179
	v_mul_f32_e32 v118, v118, v164
	v_mul_f32_e32 v118, v119, v118
	v_cndmask_b32_e64 v224, v162, 0, vcc
	v_cndmask_b32_e64 v164, v162, v122, s[34:35]
	v_cndmask_b32_e64 v179, v158, v114, s[34:35]
	v_fma_f32 v119, v162, v130, v138
	v_fmac_f32_dpp v119, v224, v126 row_ror:1 row_mask:0xf bank_mask:0xf bound_ctrl:1
	v_fmac_f32_dpp v119, v164, v134 row_ror:15 row_mask:0xf bank_mask:0xf
	v_mul_f32_e32 v178, 0xbfb8aa3b, v119
	v_exp_f32_e32 v178, v178
	v_cndmask_b32_e64 v224, v158, 0, vcc
	s_nop 1
	v_fma_f32 v164, v158, v146, v154
	v_fmac_f32_dpp v164, v224, v142 row_ror:1 row_mask:0xf bank_mask:0xf bound_ctrl:1
	v_fmac_f32_dpp v164, v179, v150 row_ror:15 row_mask:0xf bank_mask:0xf
	v_add_f32_e32 v178, 1.0, v178
	v_rcp_f32_e32 v178, v178
	s_nop 0
	v_mul_f32_e32 v119, v119, v178
	v_mul_f32_e32 v119, v164, v119
	v_cndmask_b32_e64 v224, v163, 0, vcc
	v_cndmask_b32_e64 v178, v163, v123, s[34:35]
	v_cndmask_b32_e64 v180, v159, v115, s[34:35]
	v_fma_f32 v164, v163, v131, v139
	v_fmac_f32_dpp v164, v224, v127 row_ror:1 row_mask:0xf bank_mask:0xf bound_ctrl:1
	v_fmac_f32_dpp v164, v178, v135 row_ror:15 row_mask:0xf bank_mask:0xf
	v_mul_f32_e32 v179, 0xbfb8aa3b, v164
	v_exp_f32_e32 v179, v179
	v_cndmask_b32_e64 v224, v159, 0, vcc
	v_cvt_pk_bf16_f32 v118, v117, v118
	v_add_f32_e32 v179, 1.0, v179
	v_rcp_f32_e32 v179, v179
	v_fma_f32 v178, v159, v147, v155
	v_fmac_f32_dpp v178, v224, v143 row_ror:1 row_mask:0xf bank_mask:0xf bound_ctrl:1
	v_fmac_f32_dpp v178, v180, v151 row_ror:15 row_mask:0xf bank_mask:0xf
	v_mul_f32_e32 v164, v164, v179
	v_mul_f32_e32 v164, v178, v164
	v_lshlrev_b32_e32 v178, 1, v116
	v_cvt_pk_bf16_f32 v119, v119, v164
	s_and_saveexec_b64 s[10:11], s[36:37]
	s_cbranch_execz .LBB0_1407
	v_mov_b64_e32 v[116:117], s[0:1]
	v_mad_i64_i32 v[116:117], s[38:39], v183, s66, v[116:117]
	v_lshl_add_u64 v[116:117], s[16:17], 1, v[116:117]
	s_lshl_b32 s48, s5, 1
	v_lshl_add_u64 v[116:117], v[116:117], 0, s[48:49]
	v_mov_b32_e32 v179, v165
	v_lshl_add_u64 v[116:117], v[116:117], 0, v[178:179]
	v_cvt_pk_bf16_f32 v180, v160, v161
	v_cvt_pk_bf16_f32 v181, v162, v163
	global_store_dwordx2 v[116:117], v[180:181], off
	v_cvt_pk_bf16_f32 v180, v156, v157
	v_cvt_pk_bf16_f32 v181, v158, v159
	global_store_dwordx2 v[116:117], v[180:181], off offset:256
.LBB0_1407:
	s_or_b64 exec, exec, s[10:11]
	v_cndmask_b32_e32 v224, v120, v160, vcc
	v_cndmask_b32_e64 v117, v120, v108, s[34:35]
	s_nop 0
	v_fma_f32 v116, v120, v128, v136
	v_fmac_f32_dpp v116, v224, v124 row_ror:1 row_mask:0xf bank_mask:0xf bound_ctrl:1
	v_fmac_f32_dpp v116, v117, v132 row_ror:15 row_mask:0xf bank_mask:0xf
	v_mul_f32_e32 v160, 0xbfb8aa3b, v116
	v_exp_f32_e32 v160, v160
	v_cndmask_b32_e32 v224, v112, v156, vcc
	v_cndmask_b32_e64 v156, v112, v104, s[34:35]
	s_nop 0
	v_fma_f32 v117, v112, v144, v152
	v_fmac_f32_dpp v117, v224, v140 row_ror:1 row_mask:0xf bank_mask:0xf bound_ctrl:1
	v_fmac_f32_dpp v117, v156, v148 row_ror:15 row_mask:0xf bank_mask:0xf
	v_add_f32_e32 v156, 1.0, v160
	v_rcp_f32_e32 v156, v156
	s_nop 0
	v_mul_f32_e32 v116, v116, v156
	v_mul_f32_e32 v116, v117, v116
	v_cndmask_b32_e32 v224, v121, v161, vcc
	v_cndmask_b32_e64 v156, v121, v109, s[34:35]
	s_nop 0
	v_fma_f32 v117, v121, v129, v137
	v_fmac_f32_dpp v117, v224, v125 row_ror:1 row_mask:0xf bank_mask:0xf bound_ctrl:1
	v_fmac_f32_dpp v117, v156, v133 row_ror:15 row_mask:0xf bank_mask:0xf
	v_mul_f32_e32 v160, 0xbfb8aa3b, v117
	v_exp_f32_e32 v160, v160
	v_cndmask_b32_e32 v224, v113, v157, vcc
	v_cndmask_b32_e64 v157, v113, v105, s[34:35]
	v_cndmask_b32_e32 v120, v108, v120, vcc
	v_fma_f32 v156, v113, v145, v153
	v_fmac_f32_dpp v156, v224, v141 row_ror:1 row_mask:0xf bank_mask:0xf bound_ctrl:1
	v_fmac_f32_dpp v156, v157, v149 row_ror:15 row_mask:0xf bank_mask:0xf
	v_add_f32_e32 v157, 1.0, v160
	v_rcp_f32_e32 v157, v157
	s_nop 0
	v_mul_f32_e32 v117, v117, v157
	v_mul_f32_e32 v117, v156, v117
	v_cndmask_b32_e32 v224, v122, v162, vcc
	v_cndmask_b32_e64 v157, v122, v110, s[34:35]
	s_nop 0
	v_fma_f32 v156, v122, v130, v138
	v_fmac_f32_dpp v156, v224, v126 row_ror:1 row_mask:0xf bank_mask:0xf bound_ctrl:1
	v_fmac_f32_dpp v156, v157, v134 row_ror:15 row_mask:0xf bank_mask:0xf
	v_mul_f32_e32 v160, 0xbfb8aa3b, v156
	v_exp_f32_e32 v160, v160
	v_cndmask_b32_e32 v224, v114, v158, vcc
	v_cndmask_b32_e64 v158, v114, v106, s[34:35]
	s_nop 0
	v_fma_f32 v157, v114, v146, v154
	v_fmac_f32_dpp v157, v224, v142 row_ror:1 row_mask:0xf bank_mask:0xf bound_ctrl:1
	v_fmac_f32_dpp v157, v158, v150 row_ror:15 row_mask:0xf bank_mask:0xf
	v_add_f32_e32 v158, 1.0, v160
	v_rcp_f32_e32 v158, v158
	s_nop 0
	v_mul_f32_e32 v156, v156, v158
	v_mul_f32_e32 v156, v157, v156
	v_cndmask_b32_e32 v224, v123, v163, vcc
	v_cndmask_b32_e64 v158, v123, v111, s[34:35]
	s_nop 0
	v_fma_f32 v157, v123, v131, v139
	v_fmac_f32_dpp v157, v224, v127 row_ror:1 row_mask:0xf bank_mask:0xf bound_ctrl:1
	v_fmac_f32_dpp v157, v158, v135 row_ror:15 row_mask:0xf bank_mask:0xf
	v_mul_f32_e32 v160, 0xbfb8aa3b, v157
	v_exp_f32_e32 v160, v160
	v_cndmask_b32_e32 v224, v115, v159, vcc
	v_cndmask_b32_e64 v159, v115, v107, s[34:35]
	v_cvt_pk_bf16_f32 v116, v116, v117
	v_mul_f32_dpp v120, v120, v124 row_ror:1 row_mask:0xf bank_mask:0xf bound_ctrl:1
	v_fma_f32 v158, v115, v147, v155
	v_fmac_f32_dpp v158, v224, v143 row_ror:1 row_mask:0xf bank_mask:0xf bound_ctrl:1
	v_mov_b32_dpp v161, v159 row_ror:15 row_mask:0xf bank_mask:0xf
	v_add_f32_e32 v159, 1.0, v160
	v_rcp_f32_e32 v159, v159
	v_fmac_f32_e32 v158, v151, v161
	v_mul_f32_e32 v157, v157, v159
	v_mul_f32_e32 v157, v158, v157
	v_cvt_pk_bf16_f32 v117, v156, v157
	v_cndmask_b32_e64 v156, v108, v100, s[34:35]
	v_fmac_f32_e32 v120, v108, v128
	s_nop 0
	v_fmac_f32_dpp v120, v156, v132 row_ror:15 row_mask:0xf bank_mask:0xf
	v_add_f32_e32 v120, v136, v120
	v_mul_f32_e32 v157, 0xbfb8aa3b, v120
	v_exp_f32_e32 v157, v157
	v_cndmask_b32_e64 v156, v104, v96, s[34:35]
	v_cndmask_b32_e32 v224, v104, v112, vcc
	v_cndmask_b32_e32 v225, v105, v113, vcc
	v_mov_b32_dpp v158, v156 row_ror:15 row_mask:0xf bank_mask:0xf
	v_add_f32_e32 v156, 1.0, v157
	v_rcp_f32_e32 v156, v156
	v_fma_f32 v112, v104, v144, v152
	v_fmac_f32_dpp v112, v224, v140 row_ror:1 row_mask:0xf bank_mask:0xf bound_ctrl:1
	v_fmac_f32_e32 v112, v148, v158
	v_mul_f32_e32 v120, v120, v156
	v_mul_f32_e32 v112, v112, v120
	v_cndmask_b32_e32 v224, v109, v121, vcc
	v_cndmask_b32_e64 v121, v109, v101, s[34:35]
	s_nop 0
	v_fma_f32 v120, v109, v129, v137
	v_fmac_f32_dpp v120, v224, v125 row_ror:1 row_mask:0xf bank_mask:0xf bound_ctrl:1
	v_fmac_f32_dpp v120, v121, v133 row_ror:15 row_mask:0xf bank_mask:0xf
	v_mul_f32_e32 v156, 0xbfb8aa3b, v120
	v_exp_f32_e32 v156, v156
	v_cndmask_b32_e64 v121, v105, v97, s[34:35]
	v_fma_f32 v113, v105, v145, v153
	v_fmac_f32_dpp v113, v225, v141 row_ror:1 row_mask:0xf bank_mask:0xf bound_ctrl:1
	v_mov_b32_dpp v157, v121 row_ror:15 row_mask:0xf bank_mask:0xf
	v_add_f32_e32 v121, 1.0, v156
	v_rcp_f32_e32 v121, v121
	v_fmac_f32_e32 v113, v149, v157
	v_mul_f32_e32 v120, v120, v121
	v_mul_f32_e32 v113, v113, v120
	v_cndmask_b32_e32 v224, v110, v122, vcc
	v_cndmask_b32_e64 v121, v110, v102, s[34:35]
	s_nop 0
	v_fma_f32 v120, v110, v130, v138
	v_fmac_f32_dpp v120, v224, v126 row_ror:1 row_mask:0xf bank_mask:0xf bound_ctrl:1
	v_fmac_f32_dpp v120, v121, v134 row_ror:15 row_mask:0xf bank_mask:0xf
	v_mul_f32_e32 v122, 0xbfb8aa3b, v120
	v_exp_f32_e32 v122, v122
	v_cndmask_b32_e64 v121, v106, v98, s[34:35]
	v_cndmask_b32_e32 v224, v106, v114, vcc
	v_cndmask_b32_e32 v225, v107, v115, vcc
	s_nop 0
	v_fma_f32 v114, v106, v146, v154
	v_fmac_f32_dpp v114, v224, v142 row_ror:1 row_mask:0xf bank_mask:0xf bound_ctrl:1
	v_fmac_f32_dpp v114, v121, v150 row_ror:15 row_mask:0xf bank_mask:0xf
	v_add_f32_e32 v121, 1.0, v122
	v_rcp_f32_e32 v121, v121
	s_nop 0
	v_mul_f32_e32 v120, v120, v121
	v_mul_f32_e32 v114, v114, v120
	v_cndmask_b32_e32 v224, v111, v123, vcc
	v_cndmask_b32_e64 v121, v111, v103, s[34:35]
	s_nop 0
	v_fma_f32 v120, v111, v131, v139
	v_fmac_f32_dpp v120, v224, v127 row_ror:1 row_mask:0xf bank_mask:0xf bound_ctrl:1
	v_fmac_f32_dpp v120, v121, v135 row_ror:15 row_mask:0xf bank_mask:0xf
	v_mul_f32_e32 v122, 0xbfb8aa3b, v120
	v_exp_f32_e32 v122, v122
	v_cndmask_b32_e64 v121, v107, v99, s[34:35]
	v_fma_f32 v115, v107, v147, v155
	v_fmac_f32_dpp v115, v225, v143 row_ror:1 row_mask:0xf bank_mask:0xf bound_ctrl:1
	v_fmac_f32_dpp v115, v121, v151 row_ror:15 row_mask:0xf bank_mask:0xf
	v_add_f32_e32 v121, 1.0, v122
	v_rcp_f32_e32 v121, v121
	v_cndmask_b32_e32 v224, v100, v108, vcc
	v_mul_f32_e32 v120, v120, v121
	v_mul_f32_e32 v115, v115, v120
	v_cvt_pk_bf16_f32 v112, v112, v113
	v_cvt_pk_bf16_f32 v113, v114, v115
	v_cndmask_b32_e64 v114, v100, 0, s[34:35]
	v_fma_f32 v108, v100, v128, v136
	v_fmac_f32_dpp v108, v224, v124 row_ror:1 row_mask:0xf bank_mask:0xf bound_ctrl:1
	v_fmac_f32_dpp v108, v114, v132 row_ror:15 row_mask:0xf bank_mask:0xf
	v_mul_f32_e32 v115, 0xbfb8aa3b, v108
	v_exp_f32_e32 v115, v115
	v_cndmask_b32_e64 v114, v96, 0, s[34:35]
	v_cndmask_b32_e32 v224, v96, v104, vcc
	v_cndmask_b32_e32 v225, v97, v105, vcc
	s_nop 0
	v_fma_f32 v104, v96, v144, v152
	v_fmac_f32_dpp v104, v224, v140 row_ror:1 row_mask:0xf bank_mask:0xf bound_ctrl:1
	v_fmac_f32_dpp v104, v114, v148 row_ror:15 row_mask:0xf bank_mask:0xf
	v_add_f32_e32 v114, 1.0, v115
	v_rcp_f32_e32 v114, v114
	s_nop 0
	v_mul_f32_e32 v108, v108, v114
	v_mul_f32_e32 v104, v104, v108
	v_cndmask_b32_e32 v224, v101, v109, vcc
	v_cndmask_b32_e64 v109, v101, 0, s[34:35]
	s_nop 0
	v_fma_f32 v108, v101, v129, v137
	v_fmac_f32_dpp v108, v224, v125 row_ror:1 row_mask:0xf bank_mask:0xf bound_ctrl:1
	v_fmac_f32_dpp v108, v109, v133 row_ror:15 row_mask:0xf bank_mask:0xf
	v_mul_f32_e32 v114, 0xbfb8aa3b, v108
	v_exp_f32_e32 v114, v114
	v_cndmask_b32_e64 v109, v97, 0, s[34:35]
	v_fma_f32 v105, v97, v145, v153
	v_fmac_f32_dpp v105, v225, v141 row_ror:1 row_mask:0xf bank_mask:0xf bound_ctrl:1
	v_fmac_f32_dpp v105, v109, v149 row_ror:15 row_mask:0xf bank_mask:0xf
	v_add_f32_e32 v109, 1.0, v114
	v_rcp_f32_e32 v109, v109
	s_nop 0
	v_mul_f32_e32 v108, v108, v109
	v_mul_f32_e32 v105, v105, v108
	v_cndmask_b32_e32 v224, v102, v110, vcc
	v_cndmask_b32_e64 v109, v102, 0, s[34:35]
	s_nop 0
	v_fma_f32 v108, v102, v130, v138
	v_fmac_f32_dpp v108, v224, v126 row_ror:1 row_mask:0xf bank_mask:0xf bound_ctrl:1
	v_fmac_f32_dpp v108, v109, v134 row_ror:15 row_mask:0xf bank_mask:0xf
	v_mul_f32_e32 v110, 0xbfb8aa3b, v108
	v_exp_f32_e32 v110, v110
	v_cndmask_b32_e64 v109, v98, 0, s[34:35]
	v_cndmask_b32_e32 v224, v98, v106, vcc
	v_cndmask_b32_e32 v225, v99, v107, vcc
	s_nop 0
	v_fma_f32 v106, v98, v146, v154
	v_fmac_f32_dpp v106, v224, v142 row_ror:1 row_mask:0xf bank_mask:0xf bound_ctrl:1
	v_fmac_f32_dpp v106, v109, v150 row_ror:15 row_mask:0xf bank_mask:0xf
	v_add_f32_e32 v109, 1.0, v110
	v_rcp_f32_e32 v109, v109
	s_nop 0
	v_mul_f32_e32 v108, v108, v109
	v_mul_f32_e32 v106, v106, v108
	v_cndmask_b32_e32 v224, v103, v111, vcc
	v_cndmask_b32_e64 v109, v103, 0, s[34:35]
	s_nop 0
	v_fma_f32 v108, v103, v131, v139
	v_fmac_f32_dpp v108, v224, v127 row_ror:1 row_mask:0xf bank_mask:0xf bound_ctrl:1
	v_fmac_f32_dpp v108, v109, v135 row_ror:15 row_mask:0xf bank_mask:0xf
	v_mul_f32_e32 v110, 0xbfb8aa3b, v108
	v_exp_f32_e32 v110, v110
	v_cndmask_b32_e64 v109, v99, 0, s[34:35]
	v_fma_f32 v107, v99, v147, v155
	v_fmac_f32_dpp v107, v225, v143 row_ror:1 row_mask:0xf bank_mask:0xf bound_ctrl:1
	v_fmac_f32_dpp v107, v109, v151 row_ror:15 row_mask:0xf bank_mask:0xf
	v_add_f32_e32 v109, 1.0, v110
	v_rcp_f32_e32 v109, v109
	v_cmp_lt_u32_e64 s[38:39], 13, v200
	v_add_u32_e32 v180, -12, v200
	v_mul_f32_e32 v108, v108, v109
	v_mul_f32_e32 v107, v107, v108
	v_cvt_pk_bf16_f32 v104, v104, v105
	v_cvt_pk_bf16_f32 v105, v106, v107
	s_and_saveexec_b64 s[10:11], s[38:39]
	s_cbranch_execz .LBB0_1409
	v_mov_b32_e32 v181, v165
	v_lshl_add_u64 v[106:107], s[52:53], 0, v[180:181]
	v_mov_b64_e32 v[108:109], s[0:1]
	s_movk_i32 s48, 0x2c00
	v_mad_u64_u32 v[108:109], s[40:41], v106, s48, v[108:109]
	v_mad_i32_i24 v109, v107, s48, v109
	v_lshl_add_u64 v[106:107], s[16:17], 1, v[108:109]
	s_lshl_b32 s48, s5, 1
	v_lshl_add_u64 v[106:107], v[106:107], 0, s[48:49]
	v_mov_b32_e32 v179, v165
	s_movk_i32 s66, 0x2c00
	v_lshl_add_u64 v[106:107], v[106:107], 0, v[178:179]
	v_cvt_pk_bf16_f32 v100, v100, v101
	v_cvt_pk_bf16_f32 v101, v102, v103
	global_store_dwordx2 v[106:107], v[100:101], off
	v_cvt_pk_bf16_f32 v96, v96, v97
	v_cvt_pk_bf16_f32 v97, v98, v99
	global_store_dwordx2 v[106:107], v[96:97], off offset:256
.LBB0_1409:
	s_or_b64 exec, exec, s[10:11]
	v_cndmask_b32_e64 v224, v92, 0, vcc
	v_cndmask_b32_e64 v97, v92, v84, s[34:35]
	s_nop 0
	v_fma_f32 v96, v92, v128, v136
	v_fmac_f32_dpp v96, v224, v124 row_ror:1 row_mask:0xf bank_mask:0xf bound_ctrl:1
	v_fmac_f32_dpp v96, v97, v132 row_ror:15 row_mask:0xf bank_mask:0xf
	v_mul_f32_e32 v98, 0xbfb8aa3b, v96
	v_exp_f32_e32 v98, v98
	v_cndmask_b32_e64 v224, v88, 0, vcc
	v_cndmask_b32_e64 v99, v88, v80, s[34:35]
	v_add_f32_e32 v98, 1.0, v98
	v_rcp_f32_e32 v98, v98
	v_fma_f32 v97, v88, v144, v152
	v_fmac_f32_dpp v97, v224, v140 row_ror:1 row_mask:0xf bank_mask:0xf bound_ctrl:1
	v_fmac_f32_dpp v97, v99, v148 row_ror:15 row_mask:0xf bank_mask:0xf
	v_mul_f32_e32 v96, v96, v98
	v_mul_f32_e32 v96, v97, v96
	v_cndmask_b32_e64 v224, v93, 0, vcc
	v_cndmask_b32_e64 v98, v93, v85, s[34:35]
	s_nop 0
	v_fma_f32 v97, v93, v129, v137
	v_fmac_f32_dpp v97, v224, v125 row_ror:1 row_mask:0xf bank_mask:0xf bound_ctrl:1
	v_fmac_f32_dpp v97, v98, v133 row_ror:15 row_mask:0xf bank_mask:0xf
	v_mul_f32_e32 v99, 0xbfb8aa3b, v97
	v_exp_f32_e32 v99, v99
	v_cndmask_b32_e64 v224, v89, 0, vcc
	v_cndmask_b32_e64 v100, v89, v81, s[34:35]
	v_add_f32_e32 v99, 1.0, v99
	v_rcp_f32_e32 v99, v99
	v_fma_f32 v98, v89, v145, v153
	v_fmac_f32_dpp v98, v224, v141 row_ror:1 row_mask:0xf bank_mask:0xf bound_ctrl:1
	v_fmac_f32_dpp v98, v100, v149 row_ror:15 row_mask:0xf bank_mask:0xf
	v_mul_f32_e32 v97, v97, v99
	v_mul_f32_e32 v97, v98, v97
	v_cndmask_b32_e64 v224, v94, 0, vcc
	v_cndmask_b32_e64 v99, v94, v86, s[34:35]
	s_nop 0
	v_fma_f32 v98, v94, v130, v138
	v_fmac_f32_dpp v98, v224, v126 row_ror:1 row_mask:0xf bank_mask:0xf bound_ctrl:1
	v_fmac_f32_dpp v98, v99, v134 row_ror:15 row_mask:0xf bank_mask:0xf
	v_mul_f32_e32 v100, 0xbfb8aa3b, v98
	v_exp_f32_e32 v100, v100
	v_cndmask_b32_e64 v224, v90, 0, vcc
	v_cndmask_b32_e64 v101, v90, v82, s[34:35]
	v_add_f32_e32 v100, 1.0, v100
	v_rcp_f32_e32 v100, v100
	v_fma_f32 v99, v90, v146, v154
	v_fmac_f32_dpp v99, v224, v142 row_ror:1 row_mask:0xf bank_mask:0xf bound_ctrl:1
	v_fmac_f32_dpp v99, v101, v150 row_ror:15 row_mask:0xf bank_mask:0xf
	v_mul_f32_e32 v98, v98, v100
	v_mul_f32_e32 v98, v99, v98
	v_cndmask_b32_e64 v224, v95, 0, vcc
	v_cndmask_b32_e64 v100, v95, v87, s[34:35]
	s_nop 0
	v_fma_f32 v99, v95, v131, v139
	v_fmac_f32_dpp v99, v224, v127 row_ror:1 row_mask:0xf bank_mask:0xf bound_ctrl:1
	v_fmac_f32_dpp v99, v100, v135 row_ror:15 row_mask:0xf bank_mask:0xf
	v_mul_f32_e32 v101, 0xbfb8aa3b, v99
	v_exp_f32_e32 v101, v101
	s_add_i32 s85, s31, 0x80
	v_cndmask_b32_e64 v224, v91, 0, vcc
	s_ashr_i32 s10, s85, 6
	v_add_f32_e32 v101, 1.0, v101
	v_rcp_f32_e32 v101, v101
	v_cndmask_b32_e64 v102, v91, v83, s[34:35]
	v_fma_f32 v100, v91, v147, v155
	v_fmac_f32_dpp v100, v224, v143 row_ror:1 row_mask:0xf bank_mask:0xf bound_ctrl:1
	s_ashr_i32 s11, s10, 31
	s_lshl_b64 s[10:11], s[10:11], 2
	v_fmac_f32_dpp v100, v102, v151 row_ror:15 row_mask:0xf bank_mask:0xf
	v_mul_f32_e32 v99, v99, v101
	v_or_b32_e32 v156, s10, v200
	v_mul_f32_e32 v99, v100, v99
	v_cvt_pk_bf16_f32 v96, v96, v97
	v_cvt_pk_bf16_f32 v97, v98, v99
	s_and_saveexec_b64 s[40:41], s[36:37]
	s_cbranch_execz .LBB0_1411
	v_mov_b64_e32 v[98:99], s[0:1]
	v_mad_i64_i32 v[98:99], s[86:87], v156, s66, v[98:99]
	v_lshl_add_u64 v[98:99], s[16:17], 1, v[98:99]
	s_lshl_b32 s48, s5, 1
	v_lshl_add_u64 v[98:99], v[98:99], 0, s[48:49]
	v_mov_b32_e32 v179, v165
	v_lshl_add_u64 v[98:99], v[98:99], 0, v[178:179]
	v_cvt_pk_bf16_f32 v100, v92, v93
	v_cvt_pk_bf16_f32 v101, v94, v95
	global_store_dwordx2 v[98:99], v[100:101], off
	v_cvt_pk_bf16_f32 v100, v88, v89
	v_cvt_pk_bf16_f32 v101, v90, v91
	global_store_dwordx2 v[98:99], v[100:101], off offset:256
.LBB0_1411:
	s_or_b64 exec, exec, s[40:41]
	v_cndmask_b32_e32 v224, v84, v92, vcc
	v_cndmask_b32_e64 v98, v84, v76, s[34:35]
	s_nop 0
	v_fma_f32 v92, v84, v128, v136
	v_fmac_f32_dpp v92, v224, v124 row_ror:1 row_mask:0xf bank_mask:0xf bound_ctrl:1
	v_fmac_f32_dpp v92, v98, v132 row_ror:15 row_mask:0xf bank_mask:0xf
	v_mul_f32_e32 v99, 0xbfb8aa3b, v92
	v_exp_f32_e32 v99, v99
	v_cndmask_b32_e64 v98, v80, v72, s[34:35]
	v_cndmask_b32_e32 v224, v80, v88, vcc
	v_cndmask_b32_e32 v225, v81, v89, vcc
	s_nop 0
	v_fma_f32 v88, v80, v144, v152
	v_fmac_f32_dpp v88, v224, v140 row_ror:1 row_mask:0xf bank_mask:0xf bound_ctrl:1
	v_fmac_f32_dpp v88, v98, v148 row_ror:15 row_mask:0xf bank_mask:0xf
	v_add_f32_e32 v98, 1.0, v99
	v_rcp_f32_e32 v98, v98
	s_nop 0
	v_mul_f32_e32 v92, v92, v98
	v_mul_f32_e32 v88, v88, v92
	v_cndmask_b32_e32 v224, v85, v93, vcc
	v_cndmask_b32_e64 v93, v85, v77, s[34:35]
	s_nop 0
	v_fma_f32 v92, v85, v129, v137
	v_fmac_f32_dpp v92, v224, v125 row_ror:1 row_mask:0xf bank_mask:0xf bound_ctrl:1
	v_fmac_f32_dpp v92, v93, v133 row_ror:15 row_mask:0xf bank_mask:0xf
	v_mul_f32_e32 v98, 0xbfb8aa3b, v92
	v_exp_f32_e32 v98, v98
	v_cndmask_b32_e64 v93, v81, v73, s[34:35]
	v_fma_f32 v89, v81, v145, v153
	v_fmac_f32_dpp v89, v225, v141 row_ror:1 row_mask:0xf bank_mask:0xf bound_ctrl:1
	v_fmac_f32_dpp v89, v93, v149 row_ror:15 row_mask:0xf bank_mask:0xf
	v_add_f32_e32 v93, 1.0, v98
	v_rcp_f32_e32 v93, v93
	s_nop 0
	v_mul_f32_e32 v92, v92, v93
	v_mul_f32_e32 v89, v89, v92
	v_cndmask_b32_e32 v224, v86, v94, vcc
	v_cndmask_b32_e64 v93, v86, v78, s[34:35]
	s_nop 0
	v_fma_f32 v92, v86, v130, v138
	v_fmac_f32_dpp v92, v224, v126 row_ror:1 row_mask:0xf bank_mask:0xf bound_ctrl:1
	v_fmac_f32_dpp v92, v93, v134 row_ror:15 row_mask:0xf bank_mask:0xf
	v_mul_f32_e32 v94, 0xbfb8aa3b, v92
	v_exp_f32_e32 v94, v94
	v_cndmask_b32_e64 v93, v82, v74, s[34:35]
	v_cndmask_b32_e32 v224, v82, v90, vcc
	v_cndmask_b32_e32 v225, v83, v91, vcc
	s_nop 0
	v_fma_f32 v90, v82, v146, v154
	v_fmac_f32_dpp v90, v224, v142 row_ror:1 row_mask:0xf bank_mask:0xf bound_ctrl:1
	v_fmac_f32_dpp v90, v93, v150 row_ror:15 row_mask:0xf bank_mask:0xf
	v_add_f32_e32 v93, 1.0, v94
	v_rcp_f32_e32 v93, v93
	s_nop 0
	v_mul_f32_e32 v92, v92, v93
	v_mul_f32_e32 v90, v90, v92
	v_cndmask_b32_e32 v224, v87, v95, vcc
	v_cndmask_b32_e64 v93, v87, v79, s[34:35]
	s_nop 0
	v_fma_f32 v92, v87, v131, v139
	v_fmac_f32_dpp v92, v224, v127 row_ror:1 row_mask:0xf bank_mask:0xf bound_ctrl:1
	v_fmac_f32_dpp v92, v93, v135 row_ror:15 row_mask:0xf bank_mask:0xf
	v_mul_f32_e32 v94, 0xbfb8aa3b, v92
	v_exp_f32_e32 v94, v94
	v_cndmask_b32_e64 v93, v83, v75, s[34:35]
	v_fma_f32 v91, v83, v147, v155
	v_fmac_f32_dpp v91, v225, v143 row_ror:1 row_mask:0xf bank_mask:0xf bound_ctrl:1
	v_fmac_f32_dpp v91, v93, v151 row_ror:15 row_mask:0xf bank_mask:0xf
	v_add_f32_e32 v93, 1.0, v94
	v_rcp_f32_e32 v93, v93
	v_cndmask_b32_e32 v224, v76, v84, vcc
	v_mul_f32_e32 v92, v92, v93
	v_mul_f32_e32 v91, v91, v92
	v_cvt_pk_bf16_f32 v88, v88, v89
	v_cvt_pk_bf16_f32 v89, v90, v91
	v_cndmask_b32_e64 v90, v76, v68, s[34:35]
	v_fma_f32 v84, v76, v128, v136
	v_fmac_f32_dpp v84, v224, v124 row_ror:1 row_mask:0xf bank_mask:0xf bound_ctrl:1
	v_fmac_f32_dpp v84, v90, v132 row_ror:15 row_mask:0xf bank_mask:0xf
	v_mul_f32_e32 v91, 0xbfb8aa3b, v84
	v_exp_f32_e32 v91, v91
	v_cndmask_b32_e64 v90, v72, v64, s[34:35]
	v_cndmask_b32_e32 v224, v72, v80, vcc
	v_cndmask_b32_e32 v225, v73, v81, vcc
	s_nop 0
	v_fma_f32 v80, v72, v144, v152
	v_fmac_f32_dpp v80, v224, v140 row_ror:1 row_mask:0xf bank_mask:0xf bound_ctrl:1
	v_fmac_f32_dpp v80, v90, v148 row_ror:15 row_mask:0xf bank_mask:0xf
	v_add_f32_e32 v90, 1.0, v91
	v_rcp_f32_e32 v90, v90
	s_nop 0
	v_mul_f32_e32 v84, v84, v90
	v_mul_f32_e32 v80, v80, v84
	v_cndmask_b32_e32 v224, v77, v85, vcc
	v_cndmask_b32_e64 v85, v77, v69, s[34:35]
	s_nop 0
	v_fma_f32 v84, v77, v129, v137
	v_fmac_f32_dpp v84, v224, v125 row_ror:1 row_mask:0xf bank_mask:0xf bound_ctrl:1
	v_fmac_f32_dpp v84, v85, v133 row_ror:15 row_mask:0xf bank_mask:0xf
	v_mul_f32_e32 v90, 0xbfb8aa3b, v84
	v_exp_f32_e32 v90, v90
	v_cndmask_b32_e64 v85, v73, v65, s[34:35]
	v_fma_f32 v81, v73, v145, v153
	v_fmac_f32_dpp v81, v225, v141 row_ror:1 row_mask:0xf bank_mask:0xf bound_ctrl:1
	v_fmac_f32_dpp v81, v85, v149 row_ror:15 row_mask:0xf bank_mask:0xf
	v_add_f32_e32 v85, 1.0, v90
	v_rcp_f32_e32 v85, v85
	s_nop 0
	v_mul_f32_e32 v84, v84, v85
	v_mul_f32_e32 v81, v81, v84
	v_cndmask_b32_e32 v224, v78, v86, vcc
	v_cndmask_b32_e64 v85, v78, v70, s[34:35]
	s_nop 0
	v_fma_f32 v84, v78, v130, v138
	v_fmac_f32_dpp v84, v224, v126 row_ror:1 row_mask:0xf bank_mask:0xf bound_ctrl:1
	v_fmac_f32_dpp v84, v85, v134 row_ror:15 row_mask:0xf bank_mask:0xf
	v_mul_f32_e32 v86, 0xbfb8aa3b, v84
	v_exp_f32_e32 v86, v86
	v_cndmask_b32_e64 v85, v74, v66, s[34:35]
	v_cndmask_b32_e32 v224, v74, v82, vcc
	v_cndmask_b32_e32 v225, v75, v83, vcc
	s_nop 0
	v_fma_f32 v82, v74, v146, v154
	v_fmac_f32_dpp v82, v224, v142 row_ror:1 row_mask:0xf bank_mask:0xf bound_ctrl:1
	v_fmac_f32_dpp v82, v85, v150 row_ror:15 row_mask:0xf bank_mask:0xf
	v_add_f32_e32 v85, 1.0, v86
	v_rcp_f32_e32 v85, v85
	s_nop 0
	v_mul_f32_e32 v84, v84, v85
	v_mul_f32_e32 v82, v82, v84
	v_cndmask_b32_e32 v224, v79, v87, vcc
	v_cndmask_b32_e64 v85, v79, v71, s[34:35]
	s_nop 0
	v_fma_f32 v84, v79, v131, v139
	v_fmac_f32_dpp v84, v224, v127 row_ror:1 row_mask:0xf bank_mask:0xf bound_ctrl:1
	v_fmac_f32_dpp v84, v85, v135 row_ror:15 row_mask:0xf bank_mask:0xf
	v_mul_f32_e32 v86, 0xbfb8aa3b, v84
	v_exp_f32_e32 v86, v86
	v_cndmask_b32_e64 v85, v75, v67, s[34:35]
	v_fma_f32 v83, v75, v147, v155
	v_fmac_f32_dpp v83, v225, v143 row_ror:1 row_mask:0xf bank_mask:0xf bound_ctrl:1
	v_fmac_f32_dpp v83, v85, v151 row_ror:15 row_mask:0xf bank_mask:0xf
	v_add_f32_e32 v85, 1.0, v86
	v_rcp_f32_e32 v85, v85
	v_cndmask_b32_e32 v224, v68, v76, vcc
	v_mul_f32_e32 v84, v84, v85
	v_mul_f32_e32 v83, v83, v84
	v_cvt_pk_bf16_f32 v80, v80, v81
	v_cvt_pk_bf16_f32 v81, v82, v83
	v_cndmask_b32_e64 v82, v68, 0, s[34:35]
	v_fma_f32 v76, v68, v128, v136
	v_fmac_f32_dpp v76, v224, v124 row_ror:1 row_mask:0xf bank_mask:0xf bound_ctrl:1
	v_fmac_f32_dpp v76, v82, v132 row_ror:15 row_mask:0xf bank_mask:0xf
	v_mul_f32_e32 v83, 0xbfb8aa3b, v76
	v_exp_f32_e32 v83, v83
	v_cndmask_b32_e64 v82, v64, 0, s[34:35]
	v_cndmask_b32_e32 v224, v64, v72, vcc
	v_cndmask_b32_e32 v225, v65, v73, vcc
	s_nop 0
	v_fma_f32 v72, v64, v144, v152
	v_fmac_f32_dpp v72, v224, v140 row_ror:1 row_mask:0xf bank_mask:0xf bound_ctrl:1
	v_fmac_f32_dpp v72, v82, v148 row_ror:15 row_mask:0xf bank_mask:0xf
	v_add_f32_e32 v82, 1.0, v83
	v_rcp_f32_e32 v82, v82
	s_nop 0
	v_mul_f32_e32 v76, v76, v82
	v_mul_f32_e32 v72, v72, v76
	v_cndmask_b32_e32 v224, v69, v77, vcc
	v_cndmask_b32_e64 v77, v69, 0, s[34:35]
	s_nop 0
	v_fma_f32 v76, v69, v129, v137
	v_fmac_f32_dpp v76, v224, v125 row_ror:1 row_mask:0xf bank_mask:0xf bound_ctrl:1
	v_fmac_f32_dpp v76, v77, v133 row_ror:15 row_mask:0xf bank_mask:0xf
	v_mul_f32_e32 v82, 0xbfb8aa3b, v76
	v_exp_f32_e32 v82, v82
	v_cndmask_b32_e64 v77, v65, 0, s[34:35]
	v_fma_f32 v73, v65, v145, v153
	v_fmac_f32_dpp v73, v225, v141 row_ror:1 row_mask:0xf bank_mask:0xf bound_ctrl:1
	v_fmac_f32_dpp v73, v77, v149 row_ror:15 row_mask:0xf bank_mask:0xf
	v_add_f32_e32 v77, 1.0, v82
	v_rcp_f32_e32 v77, v77
	s_nop 0
	v_mul_f32_e32 v76, v76, v77
	v_mul_f32_e32 v73, v73, v76
	v_cndmask_b32_e32 v224, v70, v78, vcc
	v_cndmask_b32_e64 v77, v70, 0, s[34:35]
	s_nop 0
	v_fma_f32 v76, v70, v130, v138
	v_fmac_f32_dpp v76, v224, v126 row_ror:1 row_mask:0xf bank_mask:0xf bound_ctrl:1
	v_fmac_f32_dpp v76, v77, v134 row_ror:15 row_mask:0xf bank_mask:0xf
	v_mul_f32_e32 v78, 0xbfb8aa3b, v76
	v_exp_f32_e32 v78, v78
	v_cndmask_b32_e64 v77, v66, 0, s[34:35]
	v_cndmask_b32_e32 v224, v66, v74, vcc
	v_cndmask_b32_e32 v225, v67, v75, vcc
	s_nop 0
	v_fma_f32 v74, v66, v146, v154
	v_fmac_f32_dpp v74, v224, v142 row_ror:1 row_mask:0xf bank_mask:0xf bound_ctrl:1
	v_fmac_f32_dpp v74, v77, v150 row_ror:15 row_mask:0xf bank_mask:0xf
	v_add_f32_e32 v77, 1.0, v78
	v_rcp_f32_e32 v77, v77
	s_nop 0
	v_mul_f32_e32 v76, v76, v77
	v_mul_f32_e32 v74, v74, v76
	v_cndmask_b32_e32 v224, v71, v79, vcc
	v_cndmask_b32_e64 v77, v71, 0, s[34:35]
	s_nop 0
	v_fma_f32 v76, v71, v131, v139
	v_fmac_f32_dpp v76, v224, v127 row_ror:1 row_mask:0xf bank_mask:0xf bound_ctrl:1
	v_fmac_f32_dpp v76, v77, v135 row_ror:15 row_mask:0xf bank_mask:0xf
	v_mul_f32_e32 v78, 0xbfb8aa3b, v76
	v_exp_f32_e32 v78, v78
	v_cndmask_b32_e64 v77, v67, 0, s[34:35]
	v_fma_f32 v75, v67, v147, v155
	v_fmac_f32_dpp v75, v225, v143 row_ror:1 row_mask:0xf bank_mask:0xf bound_ctrl:1
	v_fmac_f32_dpp v75, v77, v151 row_ror:15 row_mask:0xf bank_mask:0xf
	v_add_f32_e32 v77, 1.0, v78
	v_rcp_f32_e32 v77, v77
	v_cvt_pk_bf16_f32 v72, v72, v73
	v_mul_f32_e32 v76, v76, v77
	v_mul_f32_e32 v75, v75, v76
	v_cvt_pk_bf16_f32 v73, v74, v75
	s_and_saveexec_b64 s[40:41], s[38:39]
	s_cbranch_execz .LBB0_1413
	v_mov_b32_e32 v181, v165
	v_lshl_add_u64 v[74:75], s[10:11], 0, v[180:181]
	v_mov_b64_e32 v[76:77], s[0:1]
	s_movk_i32 s48, 0x2c00
	v_mad_u64_u32 v[76:77], s[86:87], v74, s48, v[76:77]
	v_mad_i32_i24 v77, v75, s48, v77
	v_lshl_add_u64 v[74:75], s[16:17], 1, v[76:77]
	s_lshl_b32 s48, s5, 1
	v_lshl_add_u64 v[74:75], v[74:75], 0, s[48:49]
	v_mov_b32_e32 v179, v165
	s_movk_i32 s66, 0x2c00
	v_lshl_add_u64 v[74:75], v[74:75], 0, v[178:179]
	v_cvt_pk_bf16_f32 v68, v68, v69
	v_cvt_pk_bf16_f32 v69, v70, v71
	global_store_dwordx2 v[74:75], v[68:69], off
	v_cvt_pk_bf16_f32 v64, v64, v65
	v_cvt_pk_bf16_f32 v65, v66, v67
	global_store_dwordx2 v[74:75], v[64:65], off offset:256
.LBB0_1413:
	s_or_b64 exec, exec, s[40:41]
	v_or_b32_e32 v68, 4, v182
	v_ashrrev_i32_e32 v69, 31, v68
	v_lshlrev_b64 v[82:83], 2, v[68:69]
	global_load_dwordx4 v[64:67], v[184:185], off offset:16
	v_lshl_add_u64 v[68:69], s[58:59], 0, v[82:83]
	global_load_dwordx4 v[68:71], v[68:69], off
	v_lshl_add_u64 v[74:75], s[60:61], 0, v[82:83]
	global_load_dwordx4 v[74:77], v[74:75], off
	s_nop 0
	global_load_dwordx4 v[84:87], v[186:187], off offset:16
	v_lshl_add_u64 v[90:91], s[12:13], 0, v[82:83]
	global_load_dwordx4 v[92:95], v[90:91], off
	v_lshl_add_u64 v[90:91], s[50:51], 0, v[82:83]
	global_load_dwordx4 v[100:103], v[90:91], off
	v_lshl_add_u64 v[90:91], s[20:21], 0, v[82:83]
	global_load_dwordx4 v[108:111], v[90:91], off
	v_lshl_add_u64 v[82:83], s[44:45], 0, v[82:83]
	global_load_dwordx4 v[122:125], v[82:83], off
	v_cndmask_b32_e64 v79, v60, 0, vcc
	v_cndmask_b32_e64 v83, v60, v52, s[34:35]
	v_cndmask_b32_e64 v91, v56, v48, s[34:35]
	s_nop 0
	v_mov_b32_dpp v90, v83 row_ror:15 row_mask:0xf bank_mask:0xf
	v_cndmask_b32_e64 v83, v56, 0, vcc
	v_mov_b32_dpp v98, v91 row_ror:15 row_mask:0xf bank_mask:0xf
	v_mov_b32_e32 v106, v165
	s_ashr_i32 s40, s6, 6
	s_ashr_i32 s41, s40, 31
	s_ashr_i32 s31, s31, 8
	s_lshl_b64 s[40:41], s[40:41], 15
	v_or_b32_e32 v78, s7, v200
	v_mov_b32_e32 v107, v165
	s_add_u32 s86, s80, s40
	s_mul_hi_i32 s7, s31, 0x160000
	s_mul_i32 s31, s31, 0x160000
	v_and_b32_e32 v82, 56, v182
	v_lshlrev_b32_e32 v78, 6, v78
	s_movk_i32 s6, 0x33c0
	s_addc_u32 s87, s81, s41
	v_and_or_b32 v78, v78, s6, v82
	s_add_u32 s40, s86, s31
	s_addc_u32 s41, s87, s7
	v_lshlrev_b32_e32 v164, 1, v78
	s_waitcnt vmcnt(0)
	v_mul_f32_dpp v79, v79, v64 row_ror:1 row_mask:0xf bank_mask:0xf bound_ctrl:1
	v_fmac_f32_e32 v79, v60, v68
	v_fmac_f32_e32 v79, v74, v90
	v_add_f32_e32 v79, v84, v79
	v_mul_f32_e32 v90, 0xbfb8aa3b, v79
	v_exp_f32_e32 v90, v90
	v_mul_f32_dpp v83, v83, v92 row_ror:1 row_mask:0xf bank_mask:0xf bound_ctrl:1
	v_fmac_f32_e32 v83, v56, v100
	v_add_f32_e32 v90, 1.0, v90
	v_rcp_f32_e32 v90, v90
	v_fmac_f32_e32 v83, v108, v98
	v_add_f32_e32 v83, v122, v83
	v_cndmask_b32_e64 v98, v57, v49, s[34:35]
	v_mul_f32_e32 v79, v79, v90
	v_mul_f32_e32 v79, v83, v79
	v_cndmask_b32_e64 v224, v61, 0, vcc
	v_cndmask_b32_e64 v90, v61, v53, s[34:35]
	v_mov_b32_dpp v99, v98 row_ror:15 row_mask:0xf bank_mask:0xf
	v_fma_f32 v83, v61, v69, v85
	v_fmac_f32_dpp v83, v224, v65 row_ror:1 row_mask:0xf bank_mask:0xf bound_ctrl:1
	v_fmac_f32_dpp v83, v90, v75 row_ror:15 row_mask:0xf bank_mask:0xf
	v_mul_f32_e32 v91, 0xbfb8aa3b, v83
	v_exp_f32_e32 v91, v91
	v_cndmask_b32_e64 v224, v57, 0, vcc
	v_add_f32_e32 v91, 1.0, v91
	v_rcp_f32_e32 v91, v91
	v_fma_f32 v90, v57, v101, v123
	v_fmac_f32_dpp v90, v224, v93 row_ror:1 row_mask:0xf bank_mask:0xf bound_ctrl:1
	v_fmac_f32_e32 v90, v109, v99
	v_mul_f32_e32 v83, v83, v91
	v_mul_f32_e32 v83, v90, v83
	v_cndmask_b32_e64 v224, v62, 0, vcc
	v_cndmask_b32_e64 v91, v62, v54, s[34:35]
	v_cndmask_b32_e64 v99, v58, v50, s[34:35]
	v_fma_f32 v90, v62, v70, v86
	v_fmac_f32_dpp v90, v224, v66 row_ror:1 row_mask:0xf bank_mask:0xf bound_ctrl:1
	v_fmac_f32_dpp v90, v91, v76 row_ror:15 row_mask:0xf bank_mask:0xf
	v_mul_f32_e32 v98, 0xbfb8aa3b, v90
	v_exp_f32_e32 v98, v98
	v_cndmask_b32_e64 v224, v58, 0, vcc
	s_nop 1
	v_fma_f32 v91, v58, v102, v124
	v_fmac_f32_dpp v91, v224, v94 row_ror:1 row_mask:0xf bank_mask:0xf bound_ctrl:1
	v_fmac_f32_dpp v91, v99, v110 row_ror:15 row_mask:0xf bank_mask:0xf
	v_add_f32_e32 v98, 1.0, v98
	v_rcp_f32_e32 v98, v98
	s_nop 0
	v_mul_f32_e32 v90, v90, v98
	v_mul_f32_e32 v90, v91, v90
	v_cndmask_b32_e64 v224, v63, 0, vcc
	v_cndmask_b32_e64 v98, v63, v55, s[34:35]
	v_cndmask_b32_e64 v106, v59, v51, s[34:35]
	v_fma_f32 v91, v63, v71, v87
	v_fmac_f32_dpp v91, v224, v67 row_ror:1 row_mask:0xf bank_mask:0xf bound_ctrl:1
	v_fmac_f32_dpp v91, v98, v77 row_ror:15 row_mask:0xf bank_mask:0xf
	v_mul_f32_e32 v99, 0xbfb8aa3b, v91
	v_exp_f32_e32 v99, v99
	v_cndmask_b32_e64 v224, v59, 0, vcc
	v_cvt_pk_bf16_f32 v120, v79, v83
	v_add_f32_e32 v99, 1.0, v99
	v_rcp_f32_e32 v99, v99
	v_fma_f32 v98, v59, v103, v125
	v_fmac_f32_dpp v98, v224, v95 row_ror:1 row_mask:0xf bank_mask:0xf bound_ctrl:1
	v_fmac_f32_dpp v98, v106, v111 row_ror:15 row_mask:0xf bank_mask:0xf
	v_mul_f32_e32 v91, v91, v99
	v_mul_f32_e32 v91, v98, v91
	v_cvt_pk_bf16_f32 v121, v90, v91
	global_store_dwordx4 v164, v[118:121], s[40:41]
	s_and_saveexec_b64 s[6:7], s[36:37]
	s_cbranch_execz .LBB0_1415
	v_mov_b64_e32 v[78:79], s[0:1]
	v_mad_i64_i32 v[78:79], s[88:89], v183, s66, v[78:79]
	v_lshl_add_u64 v[78:79], s[16:17], 1, v[78:79]
	s_lshl_b32 s48, s5, 1
	v_lshl_add_u64 v[78:79], v[78:79], 0, s[48:49]
	v_mov_b32_e32 v179, v165
	v_lshl_add_u64 v[78:79], v[78:79], 0, v[178:179]
	v_cvt_pk_bf16_f32 v90, v60, v61
	v_cvt_pk_bf16_f32 v91, v62, v63
	global_store_dwordx2 v[78:79], v[90:91], off offset:8
	v_cvt_pk_bf16_f32 v90, v56, v57
	v_cvt_pk_bf16_f32 v91, v58, v59
	global_store_dwordx2 v[78:79], v[90:91], off offset:264
.LBB0_1415:
	s_or_b64 exec, exec, s[6:7]
	v_cndmask_b32_e32 v224, v52, v60, vcc
	v_cndmask_b32_e64 v83, v52, v44, s[34:35]
	s_nop 0
	v_fma_f32 v60, v52, v68, v84
	v_fmac_f32_dpp v60, v224, v64 row_ror:1 row_mask:0xf bank_mask:0xf bound_ctrl:1
	v_fmac_f32_dpp v60, v83, v74 row_ror:15 row_mask:0xf bank_mask:0xf
	v_mul_f32_e32 v90, 0xbfb8aa3b, v60
	v_exp_f32_e32 v90, v90
	v_cndmask_b32_e64 v83, v48, v40, s[34:35]
	v_cndmask_b32_e32 v224, v48, v56, vcc
	v_cndmask_b32_e32 v225, v49, v57, vcc
	s_nop 0
	v_fma_f32 v56, v48, v100, v122
	v_fmac_f32_dpp v56, v224, v92 row_ror:1 row_mask:0xf bank_mask:0xf bound_ctrl:1
	v_fmac_f32_dpp v56, v83, v108 row_ror:15 row_mask:0xf bank_mask:0xf
	v_add_f32_e32 v83, 1.0, v90
	v_rcp_f32_e32 v83, v83
	s_nop 0
	v_mul_f32_e32 v60, v60, v83
	v_mul_f32_e32 v56, v56, v60
	v_cndmask_b32_e32 v224, v53, v61, vcc
	v_cndmask_b32_e64 v61, v53, v45, s[34:35]
	s_nop 0
	v_fma_f32 v60, v53, v69, v85
	v_fmac_f32_dpp v60, v224, v65 row_ror:1 row_mask:0xf bank_mask:0xf bound_ctrl:1
	v_fmac_f32_dpp v60, v61, v75 row_ror:15 row_mask:0xf bank_mask:0xf
	v_mul_f32_e32 v83, 0xbfb8aa3b, v60
	v_exp_f32_e32 v83, v83
	v_cndmask_b32_e64 v61, v49, v41, s[34:35]
	v_fma_f32 v57, v49, v101, v123
	v_fmac_f32_dpp v57, v225, v93 row_ror:1 row_mask:0xf bank_mask:0xf bound_ctrl:1
	v_fmac_f32_dpp v57, v61, v109 row_ror:15 row_mask:0xf bank_mask:0xf
	v_add_f32_e32 v61, 1.0, v83
	v_rcp_f32_e32 v61, v61
	s_nop 0
	v_mul_f32_e32 v60, v60, v61
	v_mul_f32_e32 v57, v57, v60
	v_cndmask_b32_e32 v224, v54, v62, vcc
	v_cndmask_b32_e64 v61, v54, v46, s[34:35]
	s_nop 0
	v_fma_f32 v60, v54, v70, v86
	v_fmac_f32_dpp v60, v224, v66 row_ror:1 row_mask:0xf bank_mask:0xf bound_ctrl:1
	v_fmac_f32_dpp v60, v61, v76 row_ror:15 row_mask:0xf bank_mask:0xf
	v_mul_f32_e32 v62, 0xbfb8aa3b, v60
	v_exp_f32_e32 v62, v62
	v_cndmask_b32_e64 v61, v50, v42, s[34:35]
	v_cndmask_b32_e32 v224, v50, v58, vcc
	v_cndmask_b32_e32 v225, v44, v52, vcc
	s_nop 0
	v_fma_f32 v58, v50, v102, v124
	v_fmac_f32_dpp v58, v224, v94 row_ror:1 row_mask:0xf bank_mask:0xf bound_ctrl:1
	v_fmac_f32_dpp v58, v61, v110 row_ror:15 row_mask:0xf bank_mask:0xf
	v_add_f32_e32 v61, 1.0, v62
	v_rcp_f32_e32 v61, v61
	s_nop 0
	v_mul_f32_e32 v60, v60, v61
	v_mul_f32_e32 v58, v58, v60
	v_cndmask_b32_e32 v224, v55, v63, vcc
	v_cndmask_b32_e64 v61, v55, v47, s[34:35]
	s_nop 0
	v_fma_f32 v60, v55, v71, v87
	v_fmac_f32_dpp v60, v224, v67 row_ror:1 row_mask:0xf bank_mask:0xf bound_ctrl:1
	v_fmac_f32_dpp v60, v61, v77 row_ror:15 row_mask:0xf bank_mask:0xf
	v_mul_f32_e32 v62, 0xbfb8aa3b, v60
	v_exp_f32_e32 v62, v62
	v_cvt_pk_bf16_f32 v118, v56, v57
	v_cndmask_b32_e64 v56, v44, v36, s[34:35]
	v_fma_f32 v52, v44, v68, v84
	v_fmac_f32_dpp v52, v225, v64 row_ror:1 row_mask:0xf bank_mask:0xf bound_ctrl:1
	v_cndmask_b32_e64 v61, v51, v43, s[34:35]
	s_nop 0
	s_nop 0
	v_mov_b32_dpp v63, v61 row_ror:15 row_mask:0xf bank_mask:0xf
	v_add_f32_e32 v61, 1.0, v62
	v_fmac_f32_dpp v52, v56, v74 row_ror:15 row_mask:0xf bank_mask:0xf
	v_cndmask_b32_e32 v224, v51, v59, vcc
	v_rcp_f32_e32 v61, v61
	v_fma_f32 v59, v51, v103, v125
	v_fmac_f32_dpp v59, v224, v95 row_ror:1 row_mask:0xf bank_mask:0xf bound_ctrl:1
	v_mul_f32_e32 v57, 0xbfb8aa3b, v52
	v_exp_f32_e32 v57, v57
	v_fmac_f32_e32 v59, v111, v63
	v_mul_f32_e32 v60, v60, v61
	v_mul_f32_e32 v59, v59, v60
	v_cvt_pk_bf16_f32 v119, v58, v59
	v_cndmask_b32_e64 v56, v40, v32, s[34:35]
	v_cndmask_b32_e32 v224, v40, v48, vcc
	v_cndmask_b32_e32 v225, v41, v49, vcc
	v_mov_b32_dpp v58, v56 row_ror:15 row_mask:0xf bank_mask:0xf
	v_add_f32_e32 v56, 1.0, v57
	v_rcp_f32_e32 v56, v56
	v_fma_f32 v48, v40, v100, v122
	v_fmac_f32_dpp v48, v224, v92 row_ror:1 row_mask:0xf bank_mask:0xf bound_ctrl:1
	v_fmac_f32_e32 v48, v108, v58
	v_mul_f32_e32 v52, v52, v56
	v_mul_f32_e32 v48, v48, v52
	v_cndmask_b32_e32 v224, v45, v53, vcc
	v_cndmask_b32_e64 v53, v45, v37, s[34:35]
	s_nop 0
	v_fma_f32 v52, v45, v69, v85
	v_fmac_f32_dpp v52, v224, v65 row_ror:1 row_mask:0xf bank_mask:0xf bound_ctrl:1
	v_fmac_f32_dpp v52, v53, v75 row_ror:15 row_mask:0xf bank_mask:0xf
	v_mul_f32_e32 v56, 0xbfb8aa3b, v52
	v_exp_f32_e32 v56, v56
	v_cndmask_b32_e64 v53, v41, v33, s[34:35]
	v_fma_f32 v49, v41, v101, v123
	v_fmac_f32_dpp v49, v225, v93 row_ror:1 row_mask:0xf bank_mask:0xf bound_ctrl:1
	v_mov_b32_dpp v57, v53 row_ror:15 row_mask:0xf bank_mask:0xf
	v_add_f32_e32 v53, 1.0, v56
	v_rcp_f32_e32 v53, v53
	v_fmac_f32_e32 v49, v109, v57
	v_mul_f32_e32 v52, v52, v53
	v_mul_f32_e32 v49, v49, v52
	v_cndmask_b32_e32 v224, v46, v54, vcc
	v_cndmask_b32_e64 v53, v46, v38, s[34:35]
	s_nop 0
	v_fma_f32 v52, v46, v70, v86
	v_fmac_f32_dpp v52, v224, v66 row_ror:1 row_mask:0xf bank_mask:0xf bound_ctrl:1
	v_fmac_f32_dpp v52, v53, v76 row_ror:15 row_mask:0xf bank_mask:0xf
	v_mul_f32_e32 v54, 0xbfb8aa3b, v52
	v_exp_f32_e32 v54, v54
	v_cndmask_b32_e64 v53, v42, v34, s[34:35]
	v_cndmask_b32_e32 v224, v42, v50, vcc
	v_cndmask_b32_e32 v225, v43, v51, vcc
	v_mov_b32_dpp v56, v53 row_ror:15 row_mask:0xf bank_mask:0xf
	v_add_f32_e32 v53, 1.0, v54
	v_rcp_f32_e32 v53, v53
	v_fma_f32 v50, v42, v102, v124
	v_fmac_f32_dpp v50, v224, v94 row_ror:1 row_mask:0xf bank_mask:0xf bound_ctrl:1
	v_fmac_f32_e32 v50, v110, v56
	v_mul_f32_e32 v52, v52, v53
	v_mul_f32_e32 v50, v50, v52
	v_cndmask_b32_e32 v224, v47, v55, vcc
	v_cndmask_b32_e64 v53, v47, v39, s[34:35]
	s_nop 0
	v_fma_f32 v52, v47, v71, v87
	v_fmac_f32_dpp v52, v224, v67 row_ror:1 row_mask:0xf bank_mask:0xf bound_ctrl:1
	v_fmac_f32_dpp v52, v53, v77 row_ror:15 row_mask:0xf bank_mask:0xf
	v_mul_f32_e32 v54, 0xbfb8aa3b, v52
	v_exp_f32_e32 v54, v54
	v_cndmask_b32_e64 v53, v43, v35, s[34:35]
	v_fma_f32 v51, v43, v103, v125
	v_fmac_f32_dpp v51, v225, v95 row_ror:1 row_mask:0xf bank_mask:0xf bound_ctrl:1
	v_mov_b32_dpp v55, v53 row_ror:15 row_mask:0xf bank_mask:0xf
	v_add_f32_e32 v53, 1.0, v54
	v_rcp_f32_e32 v53, v53
	v_fmac_f32_e32 v51, v111, v55
	v_cndmask_b32_e32 v224, v36, v44, vcc
	v_mul_f32_e32 v52, v52, v53
	v_mul_f32_e32 v51, v51, v52
	v_cvt_pk_bf16_f32 v115, v50, v51
	v_cndmask_b32_e64 v50, v36, 0, s[34:35]
	v_fma_f32 v44, v36, v68, v84
	v_fmac_f32_dpp v44, v224, v64 row_ror:1 row_mask:0xf bank_mask:0xf bound_ctrl:1
	v_fmac_f32_dpp v44, v50, v74 row_ror:15 row_mask:0xf bank_mask:0xf
	v_mul_f32_e32 v51, 0xbfb8aa3b, v44
	v_exp_f32_e32 v51, v51
	v_cndmask_b32_e64 v50, v32, 0, s[34:35]
	v_cndmask_b32_e32 v224, v32, v40, vcc
	v_cndmask_b32_e32 v225, v33, v41, vcc
	v_mov_b32_dpp v52, v50 row_ror:15 row_mask:0xf bank_mask:0xf
	v_add_f32_e32 v50, 1.0, v51
	v_rcp_f32_e32 v50, v50
	v_fma_f32 v40, v32, v100, v122
	v_fmac_f32_dpp v40, v224, v92 row_ror:1 row_mask:0xf bank_mask:0xf bound_ctrl:1
	v_fmac_f32_e32 v40, v108, v52
	v_mul_f32_e32 v44, v44, v50
	v_mul_f32_e32 v40, v40, v44
	v_cndmask_b32_e32 v224, v37, v45, vcc
	v_cndmask_b32_e64 v45, v37, 0, s[34:35]
	s_nop 0
	v_fma_f32 v44, v37, v69, v85
	v_fmac_f32_dpp v44, v224, v65 row_ror:1 row_mask:0xf bank_mask:0xf bound_ctrl:1
	v_fmac_f32_dpp v44, v45, v75 row_ror:15 row_mask:0xf bank_mask:0xf
	v_mul_f32_e32 v50, 0xbfb8aa3b, v44
	v_exp_f32_e32 v50, v50
	v_cndmask_b32_e64 v45, v33, 0, s[34:35]
	v_fma_f32 v41, v33, v101, v123
	v_fmac_f32_dpp v41, v225, v93 row_ror:1 row_mask:0xf bank_mask:0xf bound_ctrl:1
	v_mov_b32_dpp v51, v45 row_ror:15 row_mask:0xf bank_mask:0xf
	v_add_f32_e32 v45, 1.0, v50
	v_rcp_f32_e32 v45, v45
	v_fmac_f32_e32 v41, v109, v51
	v_mul_f32_e32 v44, v44, v45
	v_mul_f32_e32 v41, v41, v44
	v_cndmask_b32_e32 v224, v38, v46, vcc
	v_cndmask_b32_e64 v45, v38, 0, s[34:35]
	s_nop 0
	v_fma_f32 v44, v38, v70, v86
	v_fmac_f32_dpp v44, v224, v66 row_ror:1 row_mask:0xf bank_mask:0xf bound_ctrl:1
	v_fmac_f32_dpp v44, v45, v76 row_ror:15 row_mask:0xf bank_mask:0xf
	v_mul_f32_e32 v46, 0xbfb8aa3b, v44
	v_exp_f32_e32 v46, v46
	v_cndmask_b32_e64 v45, v34, 0, s[34:35]
	v_cndmask_b32_e32 v224, v34, v42, vcc
	v_cndmask_b32_e32 v225, v35, v43, vcc
	v_mov_b32_dpp v50, v45 row_ror:15 row_mask:0xf bank_mask:0xf
	v_add_f32_e32 v45, 1.0, v46
	v_rcp_f32_e32 v45, v45
	v_fma_f32 v42, v34, v102, v124
	v_fmac_f32_dpp v42, v224, v94 row_ror:1 row_mask:0xf bank_mask:0xf bound_ctrl:1
	v_fmac_f32_e32 v42, v110, v50
	v_mul_f32_e32 v44, v44, v45
	v_mul_f32_e32 v42, v42, v44
	v_cndmask_b32_e32 v224, v39, v47, vcc
	v_cndmask_b32_e64 v45, v39, 0, s[34:35]
	s_nop 0
	v_fma_f32 v44, v39, v71, v87
	v_fmac_f32_dpp v44, v224, v67 row_ror:1 row_mask:0xf bank_mask:0xf bound_ctrl:1
	v_fmac_f32_dpp v44, v45, v77 row_ror:15 row_mask:0xf bank_mask:0xf
	v_mul_f32_e32 v46, 0xbfb8aa3b, v44
	v_exp_f32_e32 v46, v46
	v_cndmask_b32_e64 v45, v35, 0, s[34:35]
	v_fma_f32 v43, v35, v103, v125
	v_fmac_f32_dpp v43, v225, v95 row_ror:1 row_mask:0xf bank_mask:0xf bound_ctrl:1
	v_lshl_add_u64 v[78:79], s[40:41], 0, v[164:165]
	v_mov_b32_dpp v47, v45 row_ror:15 row_mask:0xf bank_mask:0xf
	v_add_f32_e32 v45, 1.0, v46
	v_rcp_f32_e32 v45, v45
	s_movk_i32 s6, 0x1000
	v_cvt_pk_bf16_f32 v114, v48, v49
	v_add_co_u32_e64 v48, s[40:41], s6, v78
	v_fmac_f32_e32 v43, v111, v47
	s_nop 0
	v_addc_co_u32_e64 v49, s[40:41], 0, v79, s[40:41]
	v_mul_f32_e32 v44, v44, v45
	global_store_dwordx4 v[78:79], v[116:119], off offset:2048
	global_store_dwordx4 v[48:49], v[112:115], off
	v_mul_f32_e32 v43, v43, v44
	v_cvt_pk_bf16_f32 v106, v40, v41
	v_cvt_pk_bf16_f32 v107, v42, v43
	global_store_dwordx4 v[48:49], v[104:107], off offset:2048
	s_and_saveexec_b64 s[40:41], s[38:39]
	s_cbranch_execz .LBB0_1417
	v_mov_b32_e32 v181, v165
	v_lshl_add_u64 v[40:41], s[52:53], 0, v[180:181]
	v_mov_b64_e32 v[42:43], s[0:1]
	s_movk_i32 s31, 0x2c00
	v_mad_u64_u32 v[42:43], s[6:7], v40, s31, v[42:43]
	v_mad_i32_i24 v43, v41, s31, v43
	v_lshl_add_u64 v[40:41], s[16:17], 1, v[42:43]
	s_lshl_b32 s48, s5, 1
	v_lshl_add_u64 v[40:41], v[40:41], 0, s[48:49]
	v_mov_b32_e32 v179, v165
	s_movk_i32 s66, 0x2c00
	v_lshl_add_u64 v[40:41], v[40:41], 0, v[178:179]
	v_cvt_pk_bf16_f32 v36, v36, v37
	v_cvt_pk_bf16_f32 v37, v38, v39
	global_store_dwordx2 v[40:41], v[36:37], off offset:8
	v_cvt_pk_bf16_f32 v32, v32, v33
	v_cvt_pk_bf16_f32 v33, v34, v35
	global_store_dwordx2 v[40:41], v[32:33], off offset:264
.LBB0_1417:
	s_or_b64 exec, exec, s[40:41]
	v_cndmask_b32_e64 v224, v28, 0, vcc
	v_cndmask_b32_e64 v34, v28, v20, s[34:35]
	s_nop 0
	v_fma_f32 v33, v28, v68, v84
	v_fmac_f32_dpp v33, v224, v64 row_ror:1 row_mask:0xf bank_mask:0xf bound_ctrl:1
	v_fmac_f32_dpp v33, v34, v74 row_ror:15 row_mask:0xf bank_mask:0xf
	v_mul_f32_e32 v35, 0xbfb8aa3b, v33
	v_exp_f32_e32 v35, v35
	v_cndmask_b32_e64 v224, v24, 0, vcc
	v_cndmask_b32_e64 v36, v24, v16, s[34:35]
	v_add_f32_e32 v35, 1.0, v35
	v_rcp_f32_e32 v35, v35
	v_fma_f32 v34, v24, v100, v122
	v_fmac_f32_dpp v34, v224, v92 row_ror:1 row_mask:0xf bank_mask:0xf bound_ctrl:1
	v_fmac_f32_dpp v34, v36, v108 row_ror:15 row_mask:0xf bank_mask:0xf
	v_mul_f32_e32 v33, v33, v35
	v_mul_f32_e32 v33, v34, v33
	v_cndmask_b32_e64 v224, v29, 0, vcc
	v_cndmask_b32_e64 v35, v29, v21, s[34:35]
	s_nop 0
	v_fma_f32 v34, v29, v69, v85
	v_fmac_f32_dpp v34, v224, v65 row_ror:1 row_mask:0xf bank_mask:0xf bound_ctrl:1
	v_fmac_f32_dpp v34, v35, v75 row_ror:15 row_mask:0xf bank_mask:0xf
	v_mul_f32_e32 v36, 0xbfb8aa3b, v34
	v_exp_f32_e32 v36, v36
	v_cndmask_b32_e64 v224, v25, 0, vcc
	v_cndmask_b32_e64 v37, v25, v17, s[34:35]
	v_add_f32_e32 v36, 1.0, v36
	v_rcp_f32_e32 v36, v36
	v_fma_f32 v35, v25, v101, v123
	v_fmac_f32_dpp v35, v224, v93 row_ror:1 row_mask:0xf bank_mask:0xf bound_ctrl:1
	v_fmac_f32_dpp v35, v37, v109 row_ror:15 row_mask:0xf bank_mask:0xf
	v_mul_f32_e32 v34, v34, v36
	v_mul_f32_e32 v34, v35, v34
	v_cndmask_b32_e64 v224, v30, 0, vcc
	v_cndmask_b32_e64 v36, v30, v22, s[34:35]
	s_nop 0
	v_fma_f32 v35, v30, v70, v86
	v_fmac_f32_dpp v35, v224, v66 row_ror:1 row_mask:0xf bank_mask:0xf bound_ctrl:1
	v_fmac_f32_dpp v35, v36, v76 row_ror:15 row_mask:0xf bank_mask:0xf
	v_mul_f32_e32 v37, 0xbfb8aa3b, v35
	v_exp_f32_e32 v37, v37
	v_cndmask_b32_e64 v224, v26, 0, vcc
	v_cndmask_b32_e64 v38, v26, v18, s[34:35]
	v_add_f32_e32 v37, 1.0, v37
	v_rcp_f32_e32 v37, v37
	v_fma_f32 v36, v26, v102, v124
	v_fmac_f32_dpp v36, v224, v94 row_ror:1 row_mask:0xf bank_mask:0xf bound_ctrl:1
	v_fmac_f32_dpp v36, v38, v110 row_ror:15 row_mask:0xf bank_mask:0xf
	v_mul_f32_e32 v35, v35, v37
	v_mul_f32_e32 v35, v36, v35
	v_cndmask_b32_e64 v224, v31, 0, vcc
	v_cndmask_b32_e64 v37, v31, v23, s[34:35]
	s_nop 0
	v_fma_f32 v36, v31, v71, v87
	v_fmac_f32_dpp v36, v224, v67 row_ror:1 row_mask:0xf bank_mask:0xf bound_ctrl:1
	v_fmac_f32_dpp v36, v37, v77 row_ror:15 row_mask:0xf bank_mask:0xf
	v_mul_f32_e32 v38, 0xbfb8aa3b, v36
	v_exp_f32_e32 v38, v38
	v_cndmask_b32_e64 v224, v27, 0, vcc
	v_or_b32_e32 v32, s85, v200
	s_ashr_i32 s6, s85, 8
	v_add_f32_e32 v38, 1.0, v38
	v_rcp_f32_e32 v38, v38
	v_cndmask_b32_e64 v39, v27, v19, s[34:35]
	v_fma_f32 v37, v27, v103, v125
	v_fmac_f32_dpp v37, v224, v95 row_ror:1 row_mask:0xf bank_mask:0xf bound_ctrl:1
	s_mul_hi_i32 s7, s6, 0x160000
	s_mul_i32 s6, s6, 0x160000
	v_mov_b32_dpp v40, v39 row_ror:15 row_mask:0xf bank_mask:0xf
	v_lshlrev_b32_e32 v32, 6, v32
	s_movk_i32 s31, 0x33c0
	v_fmac_f32_e32 v37, v111, v40
	v_and_or_b32 v32, v32, s31, v82
	s_add_u32 s40, s86, s6
	v_mul_f32_e32 v36, v36, v38
	s_addc_u32 s41, s87, s7
	v_lshlrev_b32_e32 v164, 1, v32
	v_mul_f32_e32 v36, v37, v36
	v_cvt_pk_bf16_f32 v98, v33, v34
	v_cvt_pk_bf16_f32 v99, v35, v36
	global_store_dwordx4 v164, v[96:99], s[40:41]
	s_and_saveexec_b64 s[6:7], s[36:37]
	s_cbranch_execz .LBB0_1419
	v_mov_b64_e32 v[32:33], s[0:1]
	v_mad_i64_i32 v[32:33], s[36:37], v156, s66, v[32:33]
	v_lshl_add_u64 v[32:33], s[16:17], 1, v[32:33]
	s_lshl_b32 s48, s5, 1
	v_lshl_add_u64 v[32:33], v[32:33], 0, s[48:49]
	v_mov_b32_e32 v179, v165
	v_lshl_add_u64 v[32:33], v[32:33], 0, v[178:179]
	v_cvt_pk_bf16_f32 v34, v28, v29
	v_cvt_pk_bf16_f32 v35, v30, v31
	global_store_dwordx2 v[32:33], v[34:35], off offset:8
	v_cvt_pk_bf16_f32 v34, v24, v25
	v_cvt_pk_bf16_f32 v35, v26, v27
	global_store_dwordx2 v[32:33], v[34:35], off offset:264
.LBB0_1419:
	s_or_b64 exec, exec, s[6:7]
	v_cndmask_b32_e32 v224, v20, v28, vcc
	v_cndmask_b32_e64 v34, v20, v12, s[34:35]
	s_nop 0
	v_fma_f32 v28, v20, v68, v84
	v_fmac_f32_dpp v28, v224, v64 row_ror:1 row_mask:0xf bank_mask:0xf bound_ctrl:1
	v_fmac_f32_dpp v28, v34, v74 row_ror:15 row_mask:0xf bank_mask:0xf
	v_mul_f32_e32 v35, 0xbfb8aa3b, v28
	v_exp_f32_e32 v35, v35
	v_cndmask_b32_e64 v34, v16, v8, s[34:35]
	v_cndmask_b32_e32 v224, v16, v24, vcc
	v_cndmask_b32_e32 v225, v17, v25, vcc
	v_mov_b32_dpp v36, v34 row_ror:15 row_mask:0xf bank_mask:0xf
	v_add_f32_e32 v34, 1.0, v35
	v_rcp_f32_e32 v34, v34
	v_fma_f32 v24, v16, v100, v122
	v_fmac_f32_dpp v24, v224, v92 row_ror:1 row_mask:0xf bank_mask:0xf bound_ctrl:1
	v_fmac_f32_e32 v24, v108, v36
	v_mul_f32_e32 v28, v28, v34
	v_mul_f32_e32 v24, v24, v28
	v_cndmask_b32_e32 v224, v21, v29, vcc
	v_cndmask_b32_e64 v29, v21, v13, s[34:35]
	s_nop 0
	v_fma_f32 v28, v21, v69, v85
	v_fmac_f32_dpp v28, v224, v65 row_ror:1 row_mask:0xf bank_mask:0xf bound_ctrl:1
	v_fmac_f32_dpp v28, v29, v75 row_ror:15 row_mask:0xf bank_mask:0xf
	v_mul_f32_e32 v34, 0xbfb8aa3b, v28
	v_exp_f32_e32 v34, v34
	v_cndmask_b32_e64 v29, v17, v9, s[34:35]
	v_fma_f32 v25, v17, v101, v123
	v_fmac_f32_dpp v25, v225, v93 row_ror:1 row_mask:0xf bank_mask:0xf bound_ctrl:1
	v_mov_b32_dpp v35, v29 row_ror:15 row_mask:0xf bank_mask:0xf
	v_add_f32_e32 v29, 1.0, v34
	v_rcp_f32_e32 v29, v29
	v_fmac_f32_e32 v25, v109, v35
	v_mul_f32_e32 v28, v28, v29
	v_mul_f32_e32 v25, v25, v28
	v_cndmask_b32_e32 v224, v22, v30, vcc
	v_cndmask_b32_e64 v29, v22, v14, s[34:35]
	s_nop 0
	v_fma_f32 v28, v22, v70, v86
	v_fmac_f32_dpp v28, v224, v66 row_ror:1 row_mask:0xf bank_mask:0xf bound_ctrl:1
	v_fmac_f32_dpp v28, v29, v76 row_ror:15 row_mask:0xf bank_mask:0xf
	v_mul_f32_e32 v30, 0xbfb8aa3b, v28
	v_exp_f32_e32 v30, v30
	v_cndmask_b32_e64 v29, v18, v10, s[34:35]
	v_cndmask_b32_e32 v224, v18, v26, vcc
	v_cndmask_b32_e32 v225, v12, v20, vcc
	v_mov_b32_dpp v34, v29 row_ror:15 row_mask:0xf bank_mask:0xf
	v_add_f32_e32 v29, 1.0, v30
	v_rcp_f32_e32 v29, v29
	v_fma_f32 v26, v18, v102, v124
	v_fmac_f32_dpp v26, v224, v94 row_ror:1 row_mask:0xf bank_mask:0xf bound_ctrl:1
	v_fmac_f32_e32 v26, v110, v34
	v_mul_f32_e32 v28, v28, v29
	v_mul_f32_e32 v26, v26, v28
	v_cndmask_b32_e32 v224, v23, v31, vcc
	v_cndmask_b32_e64 v29, v23, v15, s[34:35]
	s_nop 0
	v_fma_f32 v28, v23, v71, v87
	v_fmac_f32_dpp v28, v224, v67 row_ror:1 row_mask:0xf bank_mask:0xf bound_ctrl:1
	v_fmac_f32_dpp v28, v29, v77 row_ror:15 row_mask:0xf bank_mask:0xf
	v_mul_f32_e32 v30, 0xbfb8aa3b, v28
	v_exp_f32_e32 v30, v30
	v_cvt_pk_bf16_f32 v90, v24, v25
	v_cndmask_b32_e64 v24, v12, v4, s[34:35]
	v_fma_f32 v20, v12, v68, v84
	v_fmac_f32_dpp v20, v225, v64 row_ror:1 row_mask:0xf bank_mask:0xf bound_ctrl:1
	v_cndmask_b32_e64 v29, v19, v11, s[34:35]
	s_nop 0
	s_nop 0
	v_mov_b32_dpp v31, v29 row_ror:15 row_mask:0xf bank_mask:0xf
	v_add_f32_e32 v29, 1.0, v30
	v_fmac_f32_dpp v20, v24, v74 row_ror:15 row_mask:0xf bank_mask:0xf
	v_cndmask_b32_e32 v224, v19, v27, vcc
	v_rcp_f32_e32 v29, v29
	v_fma_f32 v27, v19, v103, v125
	v_fmac_f32_dpp v27, v224, v95 row_ror:1 row_mask:0xf bank_mask:0xf bound_ctrl:1
	v_mul_f32_e32 v25, 0xbfb8aa3b, v20
	v_exp_f32_e32 v25, v25
	v_fmac_f32_e32 v27, v111, v31
	v_mul_f32_e32 v28, v28, v29
	v_mul_f32_e32 v27, v27, v28
	v_cvt_pk_bf16_f32 v91, v26, v27
	v_cndmask_b32_e64 v24, v8, v0, s[34:35]
	v_cndmask_b32_e32 v224, v8, v16, vcc
	v_cndmask_b32_e32 v225, v9, v17, vcc
	v_mov_b32_dpp v26, v24 row_ror:15 row_mask:0xf bank_mask:0xf
	v_add_f32_e32 v24, 1.0, v25
	v_rcp_f32_e32 v24, v24
	v_fma_f32 v16, v8, v100, v122
	v_fmac_f32_dpp v16, v224, v92 row_ror:1 row_mask:0xf bank_mask:0xf bound_ctrl:1
	v_fmac_f32_e32 v16, v108, v26
	v_mul_f32_e32 v20, v20, v24
	v_mul_f32_e32 v16, v16, v20
	v_cndmask_b32_e32 v224, v13, v21, vcc
	v_cndmask_b32_e64 v21, v13, v5, s[34:35]
	s_nop 0
	v_fma_f32 v20, v13, v69, v85
	v_fmac_f32_dpp v20, v224, v65 row_ror:1 row_mask:0xf bank_mask:0xf bound_ctrl:1
	v_fmac_f32_dpp v20, v21, v75 row_ror:15 row_mask:0xf bank_mask:0xf
	v_mul_f32_e32 v24, 0xbfb8aa3b, v20
	v_exp_f32_e32 v24, v24
	v_cndmask_b32_e64 v21, v9, v1, s[34:35]
	v_fma_f32 v17, v9, v101, v123
	v_fmac_f32_dpp v17, v225, v93 row_ror:1 row_mask:0xf bank_mask:0xf bound_ctrl:1
	v_mov_b32_dpp v25, v21 row_ror:15 row_mask:0xf bank_mask:0xf
	v_add_f32_e32 v21, 1.0, v24
	v_rcp_f32_e32 v21, v21
	v_fmac_f32_e32 v17, v109, v25
	v_mul_f32_e32 v20, v20, v21
	v_mul_f32_e32 v17, v17, v20
	v_cndmask_b32_e32 v224, v14, v22, vcc
	v_cndmask_b32_e64 v21, v14, v6, s[34:35]
	s_nop 0
	v_fma_f32 v20, v14, v70, v86
	v_fmac_f32_dpp v20, v224, v66 row_ror:1 row_mask:0xf bank_mask:0xf bound_ctrl:1
	v_fmac_f32_dpp v20, v21, v76 row_ror:15 row_mask:0xf bank_mask:0xf
	v_mul_f32_e32 v22, 0xbfb8aa3b, v20
	v_exp_f32_e32 v22, v22
	v_cndmask_b32_e64 v21, v10, v2, s[34:35]
	v_cndmask_b32_e32 v224, v10, v18, vcc
	v_cndmask_b32_e32 v225, v11, v19, vcc
	v_mov_b32_dpp v24, v21 row_ror:15 row_mask:0xf bank_mask:0xf
	v_add_f32_e32 v21, 1.0, v22
	v_rcp_f32_e32 v21, v21
	v_fma_f32 v18, v10, v102, v124
	v_fmac_f32_dpp v18, v224, v94 row_ror:1 row_mask:0xf bank_mask:0xf bound_ctrl:1
	v_fmac_f32_e32 v18, v110, v24
	v_mul_f32_e32 v20, v20, v21
	v_mul_f32_e32 v18, v18, v20
	v_cndmask_b32_e32 v224, v15, v23, vcc
	v_cndmask_b32_e64 v21, v15, v7, s[34:35]
	s_nop 0
	v_fma_f32 v20, v15, v71, v87
	v_fmac_f32_dpp v20, v224, v67 row_ror:1 row_mask:0xf bank_mask:0xf bound_ctrl:1
	v_fmac_f32_dpp v20, v21, v77 row_ror:15 row_mask:0xf bank_mask:0xf
	v_mul_f32_e32 v22, 0xbfb8aa3b, v20
	v_exp_f32_e32 v22, v22
	v_cndmask_b32_e64 v21, v11, v3, s[34:35]
	v_fma_f32 v19, v11, v103, v125
	v_fmac_f32_dpp v19, v225, v95 row_ror:1 row_mask:0xf bank_mask:0xf bound_ctrl:1
	v_mov_b32_dpp v23, v21 row_ror:15 row_mask:0xf bank_mask:0xf
	v_add_f32_e32 v21, 1.0, v22
	v_rcp_f32_e32 v21, v21
	v_fmac_f32_e32 v19, v111, v23
	v_cndmask_b32_e32 v224, v4, v12, vcc
	v_mul_f32_e32 v20, v20, v21
	v_mul_f32_e32 v19, v19, v20
	v_cvt_pk_bf16_f32 v83, v18, v19
	v_cndmask_b32_e64 v18, v4, 0, s[34:35]
	v_fma_f32 v12, v4, v68, v84
	v_fmac_f32_dpp v12, v224, v64 row_ror:1 row_mask:0xf bank_mask:0xf bound_ctrl:1
	v_fmac_f32_dpp v12, v18, v74 row_ror:15 row_mask:0xf bank_mask:0xf
	v_mul_f32_e32 v19, 0xbfb8aa3b, v12
	v_exp_f32_e32 v19, v19
	v_cndmask_b32_e64 v18, v0, 0, s[34:35]
	v_cndmask_b32_e32 v224, v0, v8, vcc
	v_cndmask_b32_e32 v225, v1, v9, vcc
	v_mov_b32_dpp v20, v18 row_ror:15 row_mask:0xf bank_mask:0xf
	v_add_f32_e32 v18, 1.0, v19
	v_rcp_f32_e32 v18, v18
	v_fma_f32 v8, v0, v100, v122
	v_fmac_f32_dpp v8, v224, v92 row_ror:1 row_mask:0xf bank_mask:0xf bound_ctrl:1
	v_fmac_f32_e32 v8, v108, v20
	v_mul_f32_e32 v12, v12, v18
	v_mul_f32_e32 v8, v8, v12
	v_cndmask_b32_e32 v224, v5, v13, vcc
	v_cndmask_b32_e64 v13, v5, 0, s[34:35]
	s_nop 0
	v_fma_f32 v12, v5, v69, v85
	v_fmac_f32_dpp v12, v224, v65 row_ror:1 row_mask:0xf bank_mask:0xf bound_ctrl:1
	v_fmac_f32_dpp v12, v13, v75 row_ror:15 row_mask:0xf bank_mask:0xf
	v_mul_f32_e32 v18, 0xbfb8aa3b, v12
	v_exp_f32_e32 v18, v18
	v_cndmask_b32_e64 v13, v1, 0, s[34:35]
	v_fma_f32 v9, v1, v101, v123
	v_fmac_f32_dpp v9, v225, v93 row_ror:1 row_mask:0xf bank_mask:0xf bound_ctrl:1
	v_mov_b32_dpp v19, v13 row_ror:15 row_mask:0xf bank_mask:0xf
	v_add_f32_e32 v13, 1.0, v18
	v_rcp_f32_e32 v13, v13
	v_fmac_f32_e32 v9, v109, v19
	v_mul_f32_e32 v12, v12, v13
	v_mul_f32_e32 v9, v9, v12
	v_cndmask_b32_e32 v224, v6, v14, vcc
	v_cndmask_b32_e64 v13, v6, 0, s[34:35]
	s_nop 0
	v_fma_f32 v12, v6, v70, v86
	v_fmac_f32_dpp v12, v224, v66 row_ror:1 row_mask:0xf bank_mask:0xf bound_ctrl:1
	v_fmac_f32_dpp v12, v13, v76 row_ror:15 row_mask:0xf bank_mask:0xf
	v_mul_f32_e32 v14, 0xbfb8aa3b, v12
	v_exp_f32_e32 v14, v14
	v_cndmask_b32_e64 v13, v2, 0, s[34:35]
	v_cndmask_b32_e32 v224, v2, v10, vcc
	v_cndmask_b32_e32 v225, v3, v11, vcc
	v_mov_b32_dpp v18, v13 row_ror:15 row_mask:0xf bank_mask:0xf
	v_add_f32_e32 v13, 1.0, v14
	v_rcp_f32_e32 v13, v13
	v_fma_f32 v10, v2, v102, v124
	v_fmac_f32_dpp v10, v224, v94 row_ror:1 row_mask:0xf bank_mask:0xf bound_ctrl:1
	v_fmac_f32_e32 v10, v110, v18
	v_mul_f32_e32 v12, v12, v13
	v_mul_f32_e32 v10, v10, v12
	v_cndmask_b32_e32 v224, v7, v15, vcc
	v_cndmask_b32_e64 v13, v7, 0, s[34:35]
	s_nop 0
	v_fma_f32 v12, v7, v71, v87
	v_fmac_f32_dpp v12, v224, v67 row_ror:1 row_mask:0xf bank_mask:0xf bound_ctrl:1
	v_fmac_f32_dpp v12, v13, v77 row_ror:15 row_mask:0xf bank_mask:0xf
	v_mul_f32_e32 v14, 0xbfb8aa3b, v12
	v_exp_f32_e32 v14, v14
	v_cndmask_b32_e64 v13, v3, 0, s[34:35]
	v_fma_f32 v11, v3, v103, v125
	v_fmac_f32_dpp v11, v225, v95 row_ror:1 row_mask:0xf bank_mask:0xf bound_ctrl:1
	v_lshl_add_u64 v[32:33], s[40:41], 0, v[164:165]
	v_mov_b32_dpp v15, v13 row_ror:15 row_mask:0xf bank_mask:0xf
	v_add_f32_e32 v13, 1.0, v14
	v_rcp_f32_e32 v13, v13
	s_movk_i32 s6, 0x1000
	v_cvt_pk_bf16_f32 v82, v16, v17
	v_add_co_u32_e64 v16, s[36:37], s6, v32
	v_fmac_f32_e32 v11, v111, v15
	s_nop 0
	v_addc_co_u32_e64 v17, s[36:37], 0, v33, s[36:37]
	v_mul_f32_e32 v12, v12, v13
	global_store_dwordx4 v[32:33], v[88:91], off offset:2048
	global_store_dwordx4 v[16:17], v[80:83], off
	v_mul_f32_e32 v11, v11, v12
	v_cvt_pk_bf16_f32 v74, v8, v9
	v_cvt_pk_bf16_f32 v75, v10, v11
	global_store_dwordx4 v[16:17], v[72:75], off offset:2048
	s_and_saveexec_b64 s[34:35], s[38:39]
	s_cbranch_execz .LBB0_1392
	v_mov_b32_e32 v181, v165
	v_lshl_add_u64 v[8:9], s[10:11], 0, v[180:181]
	v_mov_b64_e32 v[10:11], s[0:1]
	s_movk_i32 s10, 0x2c00
	v_mad_u64_u32 v[10:11], s[6:7], v8, s10, v[10:11]
	v_mad_i32_i24 v11, v9, s10, v11
	v_lshl_add_u64 v[8:9], s[16:17], 1, v[10:11]
	s_lshl_b32 s48, s5, 1
	v_lshl_add_u64 v[8:9], v[8:9], 0, s[48:49]
	v_mov_b32_e32 v179, v165
	s_movk_i32 s66, 0x2c00
	v_lshl_add_u64 v[8:9], v[8:9], 0, v[178:179]
	v_cvt_pk_bf16_f32 v4, v4, v5
	v_cvt_pk_bf16_f32 v5, v6, v7
	global_store_dwordx2 v[8:9], v[4:5], off offset:8
	v_cvt_pk_bf16_f32 v0, v0, v1
	v_cvt_pk_bf16_f32 v1, v2, v3
	global_store_dwordx2 v[8:9], v[0:1], off offset:264
	s_branch .LBB0_1392
